# v31 plus rolling SGPR ring offsets (s98/s99) replacing the 7-op mod-3 chains at each attention M-segment head and in the staging address code
# speedup vs baseline: 1.0128x; 1.0128x over previous
; template <int NCB> __device__ __forceinline__ int v_st(int k, int c) { const int kk = k;     return ((kk >> 3) * NCB + (c >> 5)) * 512 + ((kk & 7) * 32 + (c & 31)) * 2; }
; __device__ __forceinline__ int v_rd_base(int lane) { return ((lane & 3) << 3) | (((lane >> 2) & 3) << 6) | (((lane >> 4) & 1) << 5) | (((lane >> 5) & 1) << 8); }
; template <bool MLA>
; __device__ __forceinline__ void attn_core(const bf16_t* __restrict__ Qb, const bf16_t* __restrict__ Kh, const bf16_t* __restrict__ Vh, int seq, char* lds,
;                                           f32x16 (&o)[Cfg<MLA>::NCB], const int wid  , const int g  ) {
;     ...
;     float m2 = 0.f, l_reg = 0.f; f32x16 negm = f32x16{}; bf16x8 qr[NQ];
; #pragma unroll
;     for (int d = 0; d < NCB; ++d) o[d] = f32x16{};
;     const bf16_t* Qw = Qb + (long)(wid * 32 + r32) * LDQ + hi * 8;
; #pragma unroll
;     for (int d0 = 0; d0 < NQ; ++d0) qr[d0] = *reinterpret_cast<const bf16x8*>(Qw + d0 * 16);
;     const int vr0 = MLA ? (tid >> 3) : (tid >> 4), vc0 = MLA ? (tid & 7) * 8 : (tid & 15) * 8;
;     const int vst0 = v_st<NCB>(vr0, vc0), vst1 = v_st<NCB>(32 + vr0, vc0);
;     const int kcA = tid, krA = MLA ? (kcA / 12) : (tid >> 3), kcolA = MLA ? (kcA % 12) * 8 : (tid & 7) * 8;
;     const int kcB = 512 + (tid & 255), krB = kcB / 12, kcolB = (kcB % 12) * 8;
;     const int kstA = kswz<MLA>(krA, kcolA * 2), kstB = kswz<MLA>(krB, kcolB * 2);
;     const int vb0 = (int)(uintptr_t)V_lds + v_rd_base(lane);
.LBB0_1148:
	v_lshlrev_b32_e32 v6, 1, v1
	v_and_b32_e32 v6, 32, v6
	s_cmp_lg_u32 0, -1
	v_and_or_b32 v5, v5, s79, v6
	v_and_b32_e32 v3, 0x100, v3
	s_cselect_b32 s0, 0, 0
	v_lshlrev_b32_e32 v213, 4, v2
	v_mul_u32_u24_e32 v2, 0x90, v0
	s_add_i32 s7, 0, 0x10000
	v_mov_b32_e32 v14, v201
	v_mov_b32_e32 v15, v201
	v_or3_b32 v216, v5, v3, v4
	v_cmp_gt_u32_e64 s[4:5], 32, v1
	v_lshl_add_u32 v214, v0, 2, s42
	v_add3_u32 v218, s7, v2, v213
	v_mov_b32_e32 v0, v201
	v_mov_b32_e32 v1, v201
	v_mov_b32_e32 v2, v201
	v_mov_b32_e32 v3, v201
	v_mov_b32_e32 v4, v201
	v_mov_b32_e32 v5, v201
	v_mov_b32_e32 v6, v201
	v_mov_b32_e32 v7, v201
	v_mov_b32_e32 v8, v201
	v_mov_b32_e32 v9, v201
	v_mov_b32_e32 v10, v201
	v_mov_b32_e32 v11, v201
	v_mov_b32_e32 v12, v201
	v_mov_b32_e32 v13, v201
	v_mov_b64_e32 v[30:31], v[14:15]
	v_mov_b64_e32 v[46:47], v[14:15]
	v_mov_b64_e32 v[62:63], v[14:15]
	v_mov_b64_e32 v[78:79], v[14:15]
	v_mov_b32_e32 v203, v201
	s_mov_b32 s51, 0
	v_add_u32_e32 v217, s0, v216
	v_mov_b32_e32 v215, 0
	s_mov_b32 s94, 3
	v_mov_b64_e32 v[28:29], v[12:13]
	v_mov_b64_e32 v[26:27], v[10:11]
	v_mov_b64_e32 v[24:25], v[8:9]
	v_mov_b64_e32 v[22:23], v[6:7]
	v_mov_b64_e32 v[20:21], v[4:5]
	v_mov_b64_e32 v[18:19], v[2:3]
	v_mov_b64_e32 v[16:17], v[0:1]
	v_mov_b64_e32 v[44:45], v[12:13]
	v_mov_b64_e32 v[42:43], v[10:11]
	v_mov_b64_e32 v[40:41], v[8:9]
	v_mov_b64_e32 v[38:39], v[6:7]
	v_mov_b64_e32 v[36:37], v[4:5]
	v_mov_b64_e32 v[34:35], v[2:3]
	v_mov_b64_e32 v[32:33], v[0:1]
	v_mov_b64_e32 v[60:61], v[12:13]
	v_mov_b64_e32 v[58:59], v[10:11]
	v_mov_b64_e32 v[56:57], v[8:9]
	v_mov_b64_e32 v[54:55], v[6:7]
	v_mov_b64_e32 v[52:53], v[4:5]
	v_mov_b64_e32 v[50:51], v[2:3]
	v_mov_b64_e32 v[48:49], v[0:1]
	v_mov_b32_e32 v219, 0
	v_mov_b64_e32 v[76:77], v[12:13]
	v_mov_b64_e32 v[74:75], v[10:11]
	v_mov_b64_e32 v[72:73], v[8:9]
	v_mov_b64_e32 v[70:71], v[6:7]
	v_mov_b64_e32 v[68:69], v[4:5]
	v_mov_b64_e32 v[66:67], v[2:3]
	v_mov_b64_e32 v[64:65], v[0:1]
	s_mov_b32 s99, 0x4800
	s_branch .LBB0_1150

.LBB0_1150:
	s_add_i32 s95, s94, -3
	s_add_i32 s98, s99, 0x2400
	s_cmp_eq_u32 s98, 0x6c00
	s_cselect_b32 s98, 0, s98
	v_add_u32_e32 v84, s98, v218
	s_add_i32 s1, s51, 0xc000
	s_and_b32 s96, s1, 0xc000
	v_add_u32_e32 v236, s96, v217
	s_cmp_eq_u32 s51, 0
	s_cselect_b64 s[72:73], -1, 0
	ds_read_b128 v[80:83], v84
	ds_read_b128 v[224:227], v84 offset:4608
	ds_read_b128 v[220:223], v84 offset:32
	ds_read_b128 v[228:231], v84 offset:4640
	ds_read_b128 v[192:195], v84 offset:64
	ds_read_b128 v[196:199], v84 offset:4672
	ds_read_b128 v[184:187], v84 offset:96
	ds_read_b128 v[188:191], v84 offset:4704
	ds_read_b64_tr_b16 v[164:165], v236 offset:0
	ds_read_b64_tr_b16 v[166:167], v236 offset:0x800
	ds_read_b64_tr_b16 v[160:161], v236 offset:0x1000
	ds_read_b64_tr_b16 v[162:163], v236 offset:0x1800
	ds_read_b64_tr_b16 v[156:157], v236 offset:0x2000
	ds_read_b64_tr_b16 v[158:159], v236 offset:0x2800
	ds_read_b64_tr_b16 v[152:153], v236 offset:0x3000
	ds_read_b64_tr_b16 v[154:155], v236 offset:0x3800
	s_waitcnt lgkmcnt(15)
	v_mfma_f32_32x32x16_bf16 v[96:111], v[80:83], v[112:115], v[64:79]
	s_waitcnt lgkmcnt(14)
	v_mfma_f32_32x32x16_bf16 v[80:95], v[224:227], v[112:115], v[64:79]
	s_waitcnt lgkmcnt(13)
	v_mfma_f32_32x32x16_bf16 v[96:111], v[220:223], v[116:119], v[96:111]
	s_waitcnt lgkmcnt(12)
	v_mfma_f32_32x32x16_bf16 v[80:95], v[228:231], v[116:119], v[80:95]
	s_waitcnt lgkmcnt(8)
	ds_read_b64_tr_b16 v[220:221], v236 offset:0x200
	ds_read_b64_tr_b16 v[222:223], v236 offset:0xa00
	ds_read_b64_tr_b16 v[224:225], v236 offset:0x1200
	ds_read_b64_tr_b16 v[226:227], v236 offset:0x1a00
	ds_read_b64_tr_b16 v[228:229], v236 offset:0x2200
	ds_read_b64_tr_b16 v[230:231], v236 offset:0x2a00
	ds_read_b64_tr_b16 v[232:233], v236 offset:0x3200
	ds_read_b64_tr_b16 v[234:235], v236 offset:0x3a00
	v_mfma_f32_32x32x16_bf16 v[96:111], v[192:195], v[120:123], v[96:111]
	v_mfma_f32_32x32x16_bf16 v[80:95], v[196:199], v[120:123], v[80:95]
	v_mfma_f32_32x32x16_bf16 v[96:111], v[184:187], v[124:127], v[96:111]
	v_mfma_f32_32x32x16_bf16 v[80:95], v[188:191], v[124:127], v[80:95]
	ds_read_b64_tr_b16 v[184:185], v236 offset:0x600
	ds_read_b64_tr_b16 v[186:187], v236 offset:0xe00
	ds_read_b64_tr_b16 v[188:189], v236 offset:0x1600
	ds_read_b64_tr_b16 v[190:191], v236 offset:0x1e00
	ds_read_b64_tr_b16 v[192:193], v236 offset:0x2600
	ds_read_b64_tr_b16 v[194:195], v236 offset:0x2e00
	ds_read_b64_tr_b16 v[196:197], v236 offset:0x3600
	ds_read_b64_tr_b16 v[198:199], v236 offset:0x3e00
	s_and_b64 vcc, exec, s[72:73]
	s_cbranch_vccnz .Ld1_a_nopv
	s_waitcnt lgkmcnt(15)
	v_mfma_f32_32x32x16_bf16 v[48:63], v[180:183], v[164:167], v[48:63]
	v_mfma_f32_32x32x16_bf16 v[48:63], v[176:179], v[160:163], v[48:63]
	v_mfma_f32_32x32x16_bf16 v[48:63], v[172:175], v[156:159], v[48:63]
	v_mfma_f32_32x32x16_bf16 v[48:63], v[168:171], v[152:155], v[48:63]
	ds_read_b64_tr_b16 v[164:165], v236 offset:0x400
	ds_read_b64_tr_b16 v[166:167], v236 offset:0xc00
	ds_read_b64_tr_b16 v[160:161], v236 offset:0x1400
	ds_read_b64_tr_b16 v[162:163], v236 offset:0x1c00
	ds_read_b64_tr_b16 v[156:157], v236 offset:0x2400
	ds_read_b64_tr_b16 v[158:159], v236 offset:0x2c00
	ds_read_b64_tr_b16 v[152:153], v236 offset:0x3400
	ds_read_b64_tr_b16 v[154:155], v236 offset:0x3c00
	s_waitcnt lgkmcnt(15)
	v_mfma_f32_32x32x16_bf16 v[32:47], v[180:183], v[220:223], v[32:47]
	v_mfma_f32_32x32x16_bf16 v[32:47], v[176:179], v[224:227], v[32:47]
	v_mfma_f32_32x32x16_bf16 v[32:47], v[172:175], v[228:231], v[32:47]
	v_mfma_f32_32x32x16_bf16 v[32:47], v[168:171], v[232:235], v[32:47]
	s_waitcnt lgkmcnt(8)
	v_mfma_f32_32x32x16_bf16 v[0:15], v[180:183], v[184:187], v[0:15]
	v_mfma_f32_32x32x16_bf16 v[0:15], v[176:179], v[188:191], v[0:15]
	v_mfma_f32_32x32x16_bf16 v[0:15], v[172:175], v[192:195], v[0:15]
	v_mfma_f32_32x32x16_bf16 v[0:15], v[168:171], v[196:199], v[0:15]
	s_waitcnt lgkmcnt(0)
	v_mfma_f32_32x32x16_bf16 v[16:31], v[180:183], v[164:167], v[16:31]
	v_mfma_f32_32x32x16_bf16 v[16:31], v[176:179], v[160:163], v[16:31]
	v_mfma_f32_32x32x16_bf16 v[16:31], v[172:175], v[156:159], v[16:31]
	v_mfma_f32_32x32x16_bf16 v[16:31], v[168:171], v[152:155], v[16:31]

; #define SBAR() __builtin_amdgcn_sched_barrier(0)
; #define PK4(P, BASE, OUT) do { u32x4 w = {cvtpk_a(P[BASE + 0], P[BASE + 1]), cvtpk_a(P[BASE + 2], P[BASE + 3]), cvtpk_a(P[BASE + 4], P[BASE + 5]), cvtpk_a(P[BASE + 6], P[BASE + 7])}; \
;     OUT = *reinterpret_cast<bf16x8*>(&w); } while (0)
; #define SWAIT() asm volatile("s_waitcnt vmcnt(3)" ::: "memory")
; __device__ __forceinline__ float exp_pack(f32x16& p0, f32x16& p1, bf16x8& pa0, bf16x8& pa1, bf16x8& pa2, bf16x8& pa3) {
; #pragma unroll
;     for (int r = 0; r < 16; ++r) p0[r] = __builtin_amdgcn_exp2f(p0[r]);
; #pragma unroll
;     for (int r = 0; r < 16; ++r) p1[r] = __builtin_amdgcn_exp2f(p1[r]);
;     SBAR(); asm volatile("s_nop 1" ::: "memory"); SBAR();
;     ...
;     PK4(p0, 0, pa0); PK4(p0, 8, pa1); PK4(p1, 0, pa2); PK4(p1, 8, pa3);
;     ...
;     float ps0 = p0[0], ps1 = p1[0];
; #pragma unroll
;     for (int r = 1; r < 16; ++r) { ps0 += p0[r]; ps1 += p1[r]; }
;     float ps = ps0 + ps1;
;     { auto rr = __builtin_amdgcn_permlane32_swap(__float_as_uint(ps), __float_as_uint(ps), false, false);
;       ps = __uint_as_float(rr[0]) + __uint_as_float(rr[1]); }
;     return ps;
; template <bool MLA>
; __device__ __forceinline__ void attn_core(const bf16_t* __restrict__ Qb, const bf16_t* __restrict__ Kh, const bf16_t* __restrict__ Vh, int seq, char* lds,
;                                           f32x16 (&o)[Cfg<MLA>::NCB], const int wid  , const int g  ) {
;     ...
;         SWAIT(); if (j + 2 < NT) SWRITE(((j + 2) % 3) * SHM_K, ((j + 2) & 3) * SHM_V, SE);
.Lsp_de0:
	v_exp_f32_e32 v80, v80
	v_cvt_pk_bf16_f32 v180, v240, v241
	v_cvt_pk_bf16_f32 v176, v248, v249
	v_exp_f32_e32 v81, v81
	v_add_f32_e32 v240, v240, v241
	v_exp_f32_e32 v82, v82
	v_add_f32_e32 v248, v248, v249
	v_add_f32_e32 v240, v242, v240
	v_exp_f32_e32 v83, v83
	v_add_f32_e32 v248, v250, v248
	v_exp_f32_e32 v84, v84
	v_cvt_pk_bf16_f32 v181, v242, v243
	v_add_f32_e32 v240, v243, v240
	v_exp_f32_e32 v85, v85
	v_add_f32_e32 v248, v251, v248
	v_exp_f32_e32 v86, v86
	v_cvt_pk_bf16_f32 v177, v250, v251
	v_add_f32_e32 v240, v244, v240
	v_exp_f32_e32 v87, v87
	v_add_f32_e32 v248, v252, v248
	v_exp_f32_e32 v88, v88
	v_cvt_pk_bf16_f32 v182, v244, v245
	v_add_f32_e32 v240, v245, v240
	v_exp_f32_e32 v89, v89
	v_add_f32_e32 v248, v253, v248
	v_exp_f32_e32 v90, v90
	v_cvt_pk_bf16_f32 v178, v252, v253
	v_add_f32_e32 v240, v246, v240
	v_exp_f32_e32 v91, v91
	v_add_f32_e32 v248, v236, v248
	v_exp_f32_e32 v92, v92
	v_cvt_pk_bf16_f32 v183, v246, v247
	v_add_f32_e32 v240, v247, v240
	v_exp_f32_e32 v93, v93
	v_add_f32_e32 v248, v237, v248
	v_exp_f32_e32 v94, v94
	v_cvt_pk_bf16_f32 v179, v236, v237
	v_add_f32_e32 v240, v240, v248
	v_exp_f32_e32 v95, v95
	v_cvt_pk_bf16_f32 v172, v80, v81
	v_cvt_pk_bf16_f32 v168, v88, v89
	v_add_f32_e32 v80, v80, v81
	v_add_f32_e32 v88, v88, v89
	v_add_f32_e32 v80, v82, v80
	v_add_f32_e32 v88, v90, v88
	v_cvt_pk_bf16_f32 v173, v82, v83
	v_add_f32_e32 v80, v83, v80
	v_add_f32_e32 v88, v91, v88
	v_cvt_pk_bf16_f32 v169, v90, v91
	v_add_f32_e32 v80, v84, v80
	v_add_f32_e32 v88, v92, v88
	v_cvt_pk_bf16_f32 v174, v84, v85
	v_add_f32_e32 v80, v85, v80
	v_add_f32_e32 v88, v93, v88
	v_cvt_pk_bf16_f32 v170, v92, v93
	v_add_f32_e32 v80, v86, v80
	v_add_f32_e32 v88, v94, v88
	v_cvt_pk_bf16_f32 v175, v86, v87
	v_add_f32_e32 v80, v87, v80
	v_add_f32_e32 v88, v95, v88
	v_cvt_pk_bf16_f32 v171, v94, v95
	v_add_f32_e32 v80, v80, v88
	v_add_f32_e32 v185, v80, v240
	s_waitcnt vmcnt(3)
	s_cmpk_gt_u32 s95, 0x81
	s_cbranch_scc1 .LBB0_1164
	s_add_i32 s0, s51, 0x8000
	s_and_b32 s0, s0, 0x8000
	s_add_i32 s0, s0, 0
	v_add_u32_e32 v80, s0, v210
	s_waitcnt vmcnt(5)
	ds_write_b128 v80, v[132:135]
	v_add_u32_e32 v80, s0, v211
	s_waitcnt vmcnt(4)
	ds_write_b128 v80, v[128:131]
	v_add_u32_e32 v80, s99, v212
	s_waitcnt vmcnt(3)
	ds_write_b128 v80, v[136:139]
; __device__ __forceinline__ float max3f(float a, float b, float c) { return __builtin_fmaxf(__builtin_fmaxf(a, b), c); }
; __device__ __forceinline__ void rowmax_adjust(f32x16& p0, f32x16& p1, float& m2, f32x16& negm, float& alpha, const bool first) {
;     constexpr float THR2 = THR * 1.4426950408889634f;
;     float pmax = max3f(p0[0], p0[1], p0[2]);
; #pragma unroll
;     for (int r = 3; r < 15; r += 2) pmax = max3f(pmax, p0[r], p0[r + 1]);
;     pmax = max3f(pmax, p0[15], p1[0]);
; #pragma unroll
;     for (int r = 1; r < 15; r += 2) pmax = max3f(pmax, p1[r], p1[r + 1]);
;     pmax = fmaxf(pmax, p1[15]);
;     { auto rr = __builtin_amdgcn_permlane32_swap(__float_as_uint(pmax), __float_as_uint(pmax), false, false);
;       pmax = fmaxf(__uint_as_float(rr[0]), __uint_as_float(rr[1])); }
;     if (!first && __builtin_expect(__all(pmax <= THR2), 1)) { alpha = 1.f; }
.LBB0_1164:
	s_min_u32 s0, s95, 0x7f
	s_lshl_b32 s0, s0, 16
	s_add_i32 s16, s0, 0x40000
	s_add_u32 s0, s58, s16
	s_addc_u32 s1, s59, 0
	global_load_dwordx4 v[132:135], v200, s[0:1]
	global_load_dwordx4 v[128:131], v202, s[0:1]
	v_lshl_add_u64 v[80:81], v[204:205], 0, s[16:17]
	global_load_dwordx4 v[136:139], v[80:81], off
	s_waitcnt lgkmcnt(0)
	s_barrier
	s_add_i32 s99, s98, 0x2400
	s_cmp_eq_u32 s99, 0x6c00
	s_cselect_b32 s99, 0, s99
	v_add_u32_e32 v84, s99, v218
	s_and_b32 s0, s51, 0x8000
	v_add_u32_e32 v187, s0, v217
	ds_read_b128 v[80:83], v84
	ds_read_b128 v[192:195], v84 offset:4608
	ds_read_b128 v[188:191], v84 offset:32
	ds_read_b128 v[196:199], v84 offset:4640
	ds_read_b128 v[220:223], v84 offset:64
	ds_read_b128 v[228:231], v84 offset:4672
	ds_read_b128 v[224:227], v84 offset:96
	ds_read_b128 v[232:235], v84 offset:4704
	ds_read_b64_tr_b16 v[164:165], v187 offset:0
	ds_read_b64_tr_b16 v[166:167], v187 offset:0x800
	ds_read_b64_tr_b16 v[160:161], v187 offset:0x1000
	ds_read_b64_tr_b16 v[162:163], v187 offset:0x1800
	ds_read_b64_tr_b16 v[156:157], v187 offset:0x2000
	ds_read_b64_tr_b16 v[158:159], v187 offset:0x2800
	ds_read_b64_tr_b16 v[152:153], v187 offset:0x3000
	ds_read_b64_tr_b16 v[154:155], v187 offset:0x3800
	s_waitcnt lgkmcnt(15)
	v_mfma_f32_32x32x16_bf16 v[96:111], v[80:83], v[112:115], v[64:79]
	s_waitcnt lgkmcnt(14)
	v_mfma_f32_32x32x16_bf16 v[80:95], v[192:195], v[112:115], v[64:79]
	s_waitcnt lgkmcnt(13)
	v_mfma_f32_32x32x16_bf16 v[96:111], v[188:191], v[116:119], v[96:111]
	s_waitcnt lgkmcnt(12)
	v_mfma_f32_32x32x16_bf16 v[80:95], v[196:199], v[116:119], v[80:95]
	s_waitcnt lgkmcnt(8)
	ds_read_b64_tr_b16 v[188:189], v187 offset:0x200
	ds_read_b64_tr_b16 v[190:191], v187 offset:0xa00
	ds_read_b64_tr_b16 v[192:193], v187 offset:0x1200
	ds_read_b64_tr_b16 v[194:195], v187 offset:0x1a00
	ds_read_b64_tr_b16 v[196:197], v187 offset:0x2200
	ds_read_b64_tr_b16 v[198:199], v187 offset:0x2a00
	ds_read_b64_tr_b16 v[236:237], v187 offset:0x3200
	ds_read_b64_tr_b16 v[238:239], v187 offset:0x3a00
	v_mfma_f32_32x32x16_bf16 v[96:111], v[220:223], v[120:123], v[96:111]
	v_mfma_f32_32x32x16_bf16 v[80:95], v[228:231], v[120:123], v[80:95]
	v_mfma_f32_32x32x16_bf16 v[96:111], v[224:227], v[124:127], v[96:111]
	v_mfma_f32_32x32x16_bf16 v[80:95], v[232:235], v[124:127], v[80:95]
	ds_read_b64_tr_b16 v[220:221], v187 offset:0x600
	ds_read_b64_tr_b16 v[222:223], v187 offset:0xe00
	ds_read_b64_tr_b16 v[224:225], v187 offset:0x1600
	ds_read_b64_tr_b16 v[226:227], v187 offset:0x1e00
	ds_read_b64_tr_b16 v[228:229], v187 offset:0x2600
	ds_read_b64_tr_b16 v[230:231], v187 offset:0x2e00
	ds_read_b64_tr_b16 v[232:233], v187 offset:0x3600
	ds_read_b64_tr_b16 v[234:235], v187 offset:0x3e00
	s_waitcnt lgkmcnt(15)
	v_mfma_f32_32x32x16_bf16 v[48:63], v[180:183], v[164:167], v[48:63]
	v_mfma_f32_32x32x16_bf16 v[48:63], v[176:179], v[160:163], v[48:63]
	v_mfma_f32_32x32x16_bf16 v[48:63], v[172:175], v[156:159], v[48:63]
	v_mfma_f32_32x32x16_bf16 v[48:63], v[168:171], v[152:155], v[48:63]
	ds_read_b64_tr_b16 v[164:165], v187 offset:0x400
	ds_read_b64_tr_b16 v[166:167], v187 offset:0xc00
	ds_read_b64_tr_b16 v[160:161], v187 offset:0x1400
	ds_read_b64_tr_b16 v[162:163], v187 offset:0x1c00
	ds_read_b64_tr_b16 v[156:157], v187 offset:0x2400
	ds_read_b64_tr_b16 v[158:159], v187 offset:0x2c00
	ds_read_b64_tr_b16 v[152:153], v187 offset:0x3400
	ds_read_b64_tr_b16 v[154:155], v187 offset:0x3c00
	s_waitcnt lgkmcnt(15)
	v_mfma_f32_32x32x16_bf16 v[32:47], v[180:183], v[188:191], v[32:47]
	v_mfma_f32_32x32x16_bf16 v[32:47], v[176:179], v[192:195], v[32:47]
	v_mfma_f32_32x32x16_bf16 v[32:47], v[172:175], v[196:199], v[32:47]
	v_mfma_f32_32x32x16_bf16 v[32:47], v[168:171], v[236:239], v[32:47]
	s_waitcnt lgkmcnt(8)
	v_mfma_f32_32x32x16_bf16 v[0:15], v[180:183], v[220:223], v[0:15]
	v_mfma_f32_32x32x16_bf16 v[0:15], v[176:179], v[224:227], v[0:15]
	v_mfma_f32_32x32x16_bf16 v[0:15], v[172:175], v[228:231], v[0:15]
	v_mfma_f32_32x32x16_bf16 v[0:15], v[168:171], v[232:235], v[0:15]
	s_waitcnt lgkmcnt(0)
	v_mfma_f32_32x32x16_bf16 v[16:31], v[180:183], v[164:167], v[16:31]
	v_mfma_f32_32x32x16_bf16 v[16:31], v[176:179], v[160:163], v[16:31]
	v_mfma_f32_32x32x16_bf16 v[16:31], v[172:175], v[156:159], v[16:31]
	v_mfma_f32_32x32x16_bf16 v[16:31], v[168:171], v[152:155], v[16:31]
	s_barrier
	v_max3_f32 v168, v96, v97, v98
	v_exp_f32_e32 v240, v96
	v_max3_f32 v169, v81, v82, v83
	v_exp_f32_e32 v241, v97
	v_max3_f32 v168, v168, v99, v100
	v_exp_f32_e32 v242, v98
	v_max3_f32 v169, v169, v84, v85
	v_exp_f32_e32 v243, v99
	v_max3_f32 v168, v168, v101, v102
	v_exp_f32_e32 v244, v100
	v_max3_f32 v169, v169, v86, v87
	v_exp_f32_e32 v245, v101
	v_max3_f32 v168, v168, v103, v104
	v_exp_f32_e32 v246, v102
	v_max3_f32 v169, v169, v88, v89
	v_exp_f32_e32 v247, v103
	v_max3_f32 v168, v168, v105, v106
	v_exp_f32_e32 v248, v104
	v_max3_f32 v169, v169, v90, v91
	v_exp_f32_e32 v249, v105
	v_max3_f32 v168, v168, v107, v108
	v_exp_f32_e32 v250, v106
	v_max3_f32 v169, v169, v92, v93
	v_exp_f32_e32 v251, v107
	v_max3_f32 v168, v168, v109, v110
	v_exp_f32_e32 v252, v108
	v_max3_f32 v169, v169, v94, v95
	v_exp_f32_e32 v253, v109
	v_max3_f32 v168, v168, v111, v80
	v_exp_f32_e32 v236, v110
	v_max_f32_e32 v168, v168, v169
	v_exp_f32_e32 v237, v111
	v_mov_b32_e32 v169, v168
	s_nop 1
	v_permlane32_swap_b32_e32 v168, v169
	v_max_f32_e32 v168, v168, v169
	v_cmp_ge_f32_e32 vcc, s83, v168
	v_mov_b32_e32 v187, 1.0
	s_cmp_eq_u64 vcc, exec
	s_cbranch_scc1 .Lsp_do0
	s_branch .LBB0_1171

; #define SBAR() __builtin_amdgcn_sched_barrier(0)
; #define PK4(P, BASE, OUT) do { u32x4 w = {cvtpk_a(P[BASE + 0], P[BASE + 1]), cvtpk_a(P[BASE + 2], P[BASE + 3]), cvtpk_a(P[BASE + 4], P[BASE + 5]), cvtpk_a(P[BASE + 6], P[BASE + 7])}; \
;     OUT = *reinterpret_cast<bf16x8*>(&w); } while (0)
; #define SWAIT() asm volatile("s_waitcnt vmcnt(3)" ::: "memory")
; __device__ __forceinline__ float exp_pack(f32x16& p0, f32x16& p1, bf16x8& pa0, bf16x8& pa1, bf16x8& pa2, bf16x8& pa3) {
; #pragma unroll
;     for (int r = 0; r < 16; ++r) p0[r] = __builtin_amdgcn_exp2f(p0[r]);
; #pragma unroll
;     for (int r = 0; r < 16; ++r) p1[r] = __builtin_amdgcn_exp2f(p1[r]);
;     SBAR(); asm volatile("s_nop 1" ::: "memory"); SBAR();
;     ...
;     PK4(p0, 0, pa0); PK4(p0, 8, pa1); PK4(p1, 0, pa2); PK4(p1, 8, pa3);
;     ...
;     float ps0 = p0[0], ps1 = p1[0];
; #pragma unroll
;     for (int r = 1; r < 16; ++r) { ps0 += p0[r]; ps1 += p1[r]; }
;     float ps = ps0 + ps1;
;     { auto rr = __builtin_amdgcn_permlane32_swap(__float_as_uint(ps), __float_as_uint(ps), false, false);
;       ps = __uint_as_float(rr[0]) + __uint_as_float(rr[1]); }
;     return ps;
; template <bool MLA>
; __device__ __forceinline__ void attn_core(const bf16_t* __restrict__ Qb, const bf16_t* __restrict__ Kh, const bf16_t* __restrict__ Vh, int seq, char* lds,
;                                           f32x16 (&o)[Cfg<MLA>::NCB], const int wid  , const int g  ) {
;     ...
;         SWAIT(); if (j + 3 < NT) SWRITE(((j + 3) % 3) * SHM_K, ((j + 3) & 3) * SHM_V, SO);
.Lsp_do0:
	v_exp_f32_e32 v80, v80
	v_cvt_pk_bf16_f32 v180, v240, v241
	v_cvt_pk_bf16_f32 v176, v248, v249
	v_exp_f32_e32 v81, v81
	v_add_f32_e32 v240, v240, v241
	v_exp_f32_e32 v82, v82
	v_add_f32_e32 v248, v248, v249
	v_add_f32_e32 v240, v242, v240
	v_exp_f32_e32 v83, v83
	v_add_f32_e32 v248, v250, v248
	v_exp_f32_e32 v84, v84
	v_cvt_pk_bf16_f32 v181, v242, v243
	v_add_f32_e32 v240, v243, v240
	v_exp_f32_e32 v85, v85
	v_add_f32_e32 v248, v251, v248
	v_exp_f32_e32 v86, v86
	v_cvt_pk_bf16_f32 v177, v250, v251
	v_add_f32_e32 v240, v244, v240
	v_exp_f32_e32 v87, v87
	v_add_f32_e32 v248, v252, v248
	v_exp_f32_e32 v88, v88
	v_cvt_pk_bf16_f32 v182, v244, v245
	v_add_f32_e32 v240, v245, v240
	v_exp_f32_e32 v89, v89
	v_add_f32_e32 v248, v253, v248
	v_exp_f32_e32 v90, v90
	v_cvt_pk_bf16_f32 v178, v252, v253
	v_add_f32_e32 v240, v246, v240
	v_exp_f32_e32 v91, v91
	v_add_f32_e32 v248, v236, v248
	v_exp_f32_e32 v92, v92
	v_cvt_pk_bf16_f32 v183, v246, v247
	v_add_f32_e32 v240, v247, v240
	v_exp_f32_e32 v93, v93
	v_add_f32_e32 v248, v237, v248
	v_exp_f32_e32 v94, v94
	v_cvt_pk_bf16_f32 v179, v236, v237
	v_add_f32_e32 v240, v240, v248
	v_exp_f32_e32 v95, v95
	v_cvt_pk_bf16_f32 v172, v80, v81
	v_cvt_pk_bf16_f32 v168, v88, v89
	v_add_f32_e32 v80, v80, v81
	v_add_f32_e32 v88, v88, v89
	v_add_f32_e32 v80, v82, v80
	v_add_f32_e32 v88, v90, v88
	v_cvt_pk_bf16_f32 v173, v82, v83
	v_add_f32_e32 v80, v83, v80
	v_add_f32_e32 v88, v91, v88
	v_cvt_pk_bf16_f32 v169, v90, v91
	v_add_f32_e32 v80, v84, v80
	v_add_f32_e32 v88, v92, v88
	v_cvt_pk_bf16_f32 v174, v84, v85
	v_add_f32_e32 v80, v85, v80
	v_add_f32_e32 v88, v93, v88
	v_cvt_pk_bf16_f32 v170, v92, v93
	v_add_f32_e32 v80, v86, v80
	v_add_f32_e32 v88, v94, v88
	v_cvt_pk_bf16_f32 v175, v86, v87
	v_add_f32_e32 v80, v87, v80
	v_add_f32_e32 v88, v95, v88
	v_cvt_pk_bf16_f32 v171, v94, v95
	v_add_f32_e32 v80, v80, v88
	v_add_f32_e32 v80, v80, v240
	s_waitcnt vmcnt(3)
	s_cmpk_gt_u32 s95, 0x80
	s_cbranch_scc1 .LBB0_1149
	s_add_i32 s0, s96, 0
	v_add_u32_e32 v82, s0, v210
	s_waitcnt vmcnt(5)
	ds_write_b128 v82, v[140:143]
	v_add_u32_e32 v82, s0, v211
	s_waitcnt vmcnt(4)
	ds_write_b128 v82, v[144:147]
	v_add_u32_e32 v82, s98, v212
	s_waitcnt vmcnt(3)
	ds_write_b128 v82, v[148:151]
	s_branch .LBB0_1149

; template <int NCB> __device__ __forceinline__ int v_st(int k, int c) { const int kk = k;     return ((kk >> 3) * NCB + (c >> 5)) * 512 + ((kk & 7) * 32 + (c & 31)) * 2; }
; __device__ __forceinline__ int v_rd_base(int lane) { return ((lane & 3) << 3) | (((lane >> 2) & 3) << 6) | (((lane >> 4) & 1) << 5) | (((lane >> 5) & 1) << 8); }
; template <bool MLA>
; __device__ __forceinline__ void attn_core(const bf16_t* __restrict__ Qb, const bf16_t* __restrict__ Kh, const bf16_t* __restrict__ Vh, int seq, char* lds,
;                                           f32x16 (&o)[Cfg<MLA>::NCB], const int wid  , const int g  ) {
;     ...
;     float m2 = 0.f, l_reg = 0.f; f32x16 negm = f32x16{}; bf16x8 qr[NQ];
; #pragma unroll
;     for (int d = 0; d < NCB; ++d) o[d] = f32x16{};
;     const bf16_t* Qw = Qb + (long)(wid * 32 + r32) * LDQ + hi * 8;
; #pragma unroll
;     for (int d0 = 0; d0 < NQ; ++d0) qr[d0] = *reinterpret_cast<const bf16x8*>(Qw + d0 * 16);
;     const int vr0 = MLA ? (tid >> 3) : (tid >> 4), vc0 = MLA ? (tid & 7) * 8 : (tid & 15) * 8;
;     const int vst0 = v_st<NCB>(vr0, vc0), vst1 = v_st<NCB>(32 + vr0, vc0);
;     const int kcA = tid, krA = MLA ? (kcA / 12) : (tid >> 3), kcolA = MLA ? (kcA % 12) * 8 : (tid & 7) * 8;
;     const int kcB = 512 + (tid & 255), krB = kcB / 12, kcolB = (kcB % 12) * 8;
;     const int kstA = kswz<MLA>(krA, kcolA * 2), kstB = kswz<MLA>(krB, kcolB * 2);
;     const int vb0 = (int)(uintptr_t)V_lds + v_rd_base(lane);
.LBB0_1179:
	s_mov_b64 s[0:1], 0x80
	v_lshl_add_u64 v[204:205], v[0:1], 0, s[0:1]
	v_lshlrev_b32_e32 v0, 1, v3
	v_and_b32_e32 v0, 32, v0
	v_and_or_b32 v0, v7, s79, v0
	v_and_b32_e32 v1, 0x100, v5
	v_or3_b32 v216, v0, v1, v6
	s_cmp_lg_u32 0, -1
	v_lshlrev_b32_e32 v213, 4, v4
	v_mul_u32_u24_e32 v0, 0x90, v2
	v_mov_b32_e32 v14, v201
	v_mov_b32_e32 v15, v201
	s_cselect_b32 s0, 0, 0
	v_cmp_gt_u32_e64 s[4:5], 32, v3
	v_lshl_add_u32 v214, v2, 2, s42
	v_add3_u32 v218, s7, v0, v213
	v_mov_b32_e32 v0, v201
	v_mov_b32_e32 v1, v201
	v_mov_b32_e32 v2, v201
	v_mov_b32_e32 v3, v201
	v_mov_b32_e32 v4, v201
	v_mov_b32_e32 v5, v201
	v_mov_b32_e32 v6, v201
	v_mov_b32_e32 v7, v201
	v_mov_b32_e32 v8, v201
	v_mov_b32_e32 v9, v201
	v_mov_b32_e32 v10, v201
	v_mov_b32_e32 v11, v201
	v_mov_b32_e32 v12, v201
	v_mov_b32_e32 v13, v201
	v_mov_b64_e32 v[30:31], v[14:15]
	v_mov_b64_e32 v[46:47], v[14:15]
	v_mov_b64_e32 v[62:63], v[14:15]
	v_mov_b64_e32 v[78:79], v[14:15]
	v_mov_b32_e32 v203, v201
	s_mov_b32 s51, 0
	v_add_u32_e32 v217, s0, v216
	v_mov_b32_e32 v215, 0
	s_mov_b32 s7, 3
	v_mov_b64_e32 v[28:29], v[12:13]
	v_mov_b64_e32 v[26:27], v[10:11]
	v_mov_b64_e32 v[24:25], v[8:9]
	v_mov_b64_e32 v[22:23], v[6:7]
	v_mov_b64_e32 v[20:21], v[4:5]
	v_mov_b64_e32 v[18:19], v[2:3]
	v_mov_b64_e32 v[16:17], v[0:1]
	v_mov_b64_e32 v[44:45], v[12:13]
	v_mov_b64_e32 v[42:43], v[10:11]
	v_mov_b64_e32 v[40:41], v[8:9]
	v_mov_b64_e32 v[38:39], v[6:7]
	v_mov_b64_e32 v[36:37], v[4:5]
	v_mov_b64_e32 v[34:35], v[2:3]
	v_mov_b64_e32 v[32:33], v[0:1]
	v_mov_b64_e32 v[60:61], v[12:13]
	v_mov_b64_e32 v[58:59], v[10:11]
	v_mov_b64_e32 v[56:57], v[8:9]
	v_mov_b64_e32 v[54:55], v[6:7]
	v_mov_b64_e32 v[52:53], v[4:5]
	v_mov_b64_e32 v[50:51], v[2:3]
	v_mov_b64_e32 v[48:49], v[0:1]
	v_mov_b32_e32 v219, 0
	v_mov_b64_e32 v[76:77], v[12:13]
	v_mov_b64_e32 v[74:75], v[10:11]
	v_mov_b64_e32 v[72:73], v[8:9]
	v_mov_b64_e32 v[70:71], v[6:7]
	v_mov_b64_e32 v[68:69], v[4:5]
	v_mov_b64_e32 v[66:67], v[2:3]
	v_mov_b64_e32 v[64:65], v[0:1]
	s_mov_b32 s99, 0x4800
	s_branch .LBB0_1181

.LBB0_1181:
	s_add_i32 s64, s7, -3
	s_add_i32 s98, s99, 0x2400
	s_cmp_eq_u32 s98, 0x6c00
	s_cselect_b32 s98, 0, s98
	v_add_u32_e32 v84, s98, v218
	s_add_i32 s1, s51, 0xc000
	s_and_b32 s65, s1, 0xc000
	v_add_u32_e32 v236, s65, v217
	s_cmp_eq_u32 s51, 0
	s_cselect_b64 s[60:61], -1, 0
	ds_read_b128 v[80:83], v84
	ds_read_b128 v[224:227], v84 offset:4608
	ds_read_b128 v[220:223], v84 offset:32
	ds_read_b128 v[228:231], v84 offset:4640
	ds_read_b128 v[192:195], v84 offset:64
	ds_read_b128 v[196:199], v84 offset:4672
	ds_read_b128 v[184:187], v84 offset:96
	ds_read_b128 v[188:191], v84 offset:4704
	ds_read_b64_tr_b16 v[164:165], v236 offset:0
	ds_read_b64_tr_b16 v[166:167], v236 offset:0x800
	ds_read_b64_tr_b16 v[160:161], v236 offset:0x1000
	ds_read_b64_tr_b16 v[162:163], v236 offset:0x1800
	ds_read_b64_tr_b16 v[156:157], v236 offset:0x2000
	ds_read_b64_tr_b16 v[158:159], v236 offset:0x2800
	ds_read_b64_tr_b16 v[152:153], v236 offset:0x3000
	ds_read_b64_tr_b16 v[154:155], v236 offset:0x3800
	s_waitcnt lgkmcnt(15)
	v_mfma_f32_32x32x16_bf16 v[96:111], v[80:83], v[112:115], v[64:79]
	s_waitcnt lgkmcnt(14)
	v_mfma_f32_32x32x16_bf16 v[80:95], v[224:227], v[112:115], v[64:79]
	s_waitcnt lgkmcnt(13)
	v_mfma_f32_32x32x16_bf16 v[96:111], v[220:223], v[116:119], v[96:111]
	s_waitcnt lgkmcnt(12)
	v_mfma_f32_32x32x16_bf16 v[80:95], v[228:231], v[116:119], v[80:95]
	s_waitcnt lgkmcnt(8)
	ds_read_b64_tr_b16 v[220:221], v236 offset:0x200
	ds_read_b64_tr_b16 v[222:223], v236 offset:0xa00
	ds_read_b64_tr_b16 v[224:225], v236 offset:0x1200
	ds_read_b64_tr_b16 v[226:227], v236 offset:0x1a00
	ds_read_b64_tr_b16 v[228:229], v236 offset:0x2200
	ds_read_b64_tr_b16 v[230:231], v236 offset:0x2a00
	ds_read_b64_tr_b16 v[232:233], v236 offset:0x3200
	ds_read_b64_tr_b16 v[234:235], v236 offset:0x3a00
	v_mfma_f32_32x32x16_bf16 v[96:111], v[192:195], v[120:123], v[96:111]
	v_mfma_f32_32x32x16_bf16 v[80:95], v[196:199], v[120:123], v[80:95]
	v_mfma_f32_32x32x16_bf16 v[96:111], v[184:187], v[124:127], v[96:111]
	v_mfma_f32_32x32x16_bf16 v[80:95], v[188:191], v[124:127], v[80:95]
	ds_read_b64_tr_b16 v[184:185], v236 offset:0x600
	ds_read_b64_tr_b16 v[186:187], v236 offset:0xe00
	ds_read_b64_tr_b16 v[188:189], v236 offset:0x1600
	ds_read_b64_tr_b16 v[190:191], v236 offset:0x1e00
	ds_read_b64_tr_b16 v[192:193], v236 offset:0x2600
	ds_read_b64_tr_b16 v[194:195], v236 offset:0x2e00
	ds_read_b64_tr_b16 v[196:197], v236 offset:0x3600
	ds_read_b64_tr_b16 v[198:199], v236 offset:0x3e00
	s_and_b64 vcc, exec, s[60:61]
	s_cbranch_vccnz .Ld1_b_nopv
	s_waitcnt lgkmcnt(15)
	v_mfma_f32_32x32x16_bf16 v[48:63], v[180:183], v[164:167], v[48:63]
	v_mfma_f32_32x32x16_bf16 v[48:63], v[176:179], v[160:163], v[48:63]
	v_mfma_f32_32x32x16_bf16 v[48:63], v[172:175], v[156:159], v[48:63]
	v_mfma_f32_32x32x16_bf16 v[48:63], v[168:171], v[152:155], v[48:63]
	ds_read_b64_tr_b16 v[164:165], v236 offset:0x400
	ds_read_b64_tr_b16 v[166:167], v236 offset:0xc00
	ds_read_b64_tr_b16 v[160:161], v236 offset:0x1400
	ds_read_b64_tr_b16 v[162:163], v236 offset:0x1c00
	ds_read_b64_tr_b16 v[156:157], v236 offset:0x2400
	ds_read_b64_tr_b16 v[158:159], v236 offset:0x2c00
	ds_read_b64_tr_b16 v[152:153], v236 offset:0x3400
	ds_read_b64_tr_b16 v[154:155], v236 offset:0x3c00
	s_waitcnt lgkmcnt(15)
	v_mfma_f32_32x32x16_bf16 v[32:47], v[180:183], v[220:223], v[32:47]
	v_mfma_f32_32x32x16_bf16 v[32:47], v[176:179], v[224:227], v[32:47]
	v_mfma_f32_32x32x16_bf16 v[32:47], v[172:175], v[228:231], v[32:47]
	v_mfma_f32_32x32x16_bf16 v[32:47], v[168:171], v[232:235], v[32:47]
	s_waitcnt lgkmcnt(8)
	v_mfma_f32_32x32x16_bf16 v[0:15], v[180:183], v[184:187], v[0:15]
	v_mfma_f32_32x32x16_bf16 v[0:15], v[176:179], v[188:191], v[0:15]
	v_mfma_f32_32x32x16_bf16 v[0:15], v[172:175], v[192:195], v[0:15]
	v_mfma_f32_32x32x16_bf16 v[0:15], v[168:171], v[196:199], v[0:15]
	s_waitcnt lgkmcnt(0)
	v_mfma_f32_32x32x16_bf16 v[16:31], v[180:183], v[164:167], v[16:31]
	v_mfma_f32_32x32x16_bf16 v[16:31], v[176:179], v[160:163], v[16:31]
	v_mfma_f32_32x32x16_bf16 v[16:31], v[172:175], v[156:159], v[16:31]
	v_mfma_f32_32x32x16_bf16 v[16:31], v[168:171], v[152:155], v[16:31]

; #define SBAR() __builtin_amdgcn_sched_barrier(0)
; #define PK4(P, BASE, OUT) do { u32x4 w = {cvtpk_a(P[BASE + 0], P[BASE + 1]), cvtpk_a(P[BASE + 2], P[BASE + 3]), cvtpk_a(P[BASE + 4], P[BASE + 5]), cvtpk_a(P[BASE + 6], P[BASE + 7])}; \
;     OUT = *reinterpret_cast<bf16x8*>(&w); } while (0)
; #define SWAIT() asm volatile("s_waitcnt vmcnt(3)" ::: "memory")
; __device__ __forceinline__ float exp_pack(f32x16& p0, f32x16& p1, bf16x8& pa0, bf16x8& pa1, bf16x8& pa2, bf16x8& pa3) {
; #pragma unroll
;     for (int r = 0; r < 16; ++r) p0[r] = __builtin_amdgcn_exp2f(p0[r]);
; #pragma unroll
;     for (int r = 0; r < 16; ++r) p1[r] = __builtin_amdgcn_exp2f(p1[r]);
;     SBAR(); asm volatile("s_nop 1" ::: "memory"); SBAR();
;     ...
;     PK4(p0, 0, pa0); PK4(p0, 8, pa1); PK4(p1, 0, pa2); PK4(p1, 8, pa3);
;     ...
;     float ps0 = p0[0], ps1 = p1[0];
; #pragma unroll
;     for (int r = 1; r < 16; ++r) { ps0 += p0[r]; ps1 += p1[r]; }
;     float ps = ps0 + ps1;
;     { auto rr = __builtin_amdgcn_permlane32_swap(__float_as_uint(ps), __float_as_uint(ps), false, false);
;       ps = __uint_as_float(rr[0]) + __uint_as_float(rr[1]); }
;     return ps;
; template <bool MLA>
; __device__ __forceinline__ void attn_core(const bf16_t* __restrict__ Qb, const bf16_t* __restrict__ Kh, const bf16_t* __restrict__ Vh, int seq, char* lds,
;                                           f32x16 (&o)[Cfg<MLA>::NCB], const int wid  , const int g  ) {
;     ...
;         SWAIT(); if (j + 2 < NT) SWRITE(((j + 2) % 3) * SHM_K, ((j + 2) & 3) * SHM_V, SE);
.Lsp_de31:
	v_exp_f32_e32 v80, v80
	v_cvt_pk_bf16_f32 v180, v240, v241
	v_cvt_pk_bf16_f32 v176, v248, v249
	v_exp_f32_e32 v81, v81
	v_add_f32_e32 v240, v240, v241
	v_exp_f32_e32 v82, v82
	v_add_f32_e32 v248, v248, v249
	v_add_f32_e32 v240, v242, v240
	v_exp_f32_e32 v83, v83
	v_add_f32_e32 v248, v250, v248
	v_exp_f32_e32 v84, v84
	v_cvt_pk_bf16_f32 v181, v242, v243
	v_add_f32_e32 v240, v243, v240
	v_exp_f32_e32 v85, v85
	v_add_f32_e32 v248, v251, v248
	v_exp_f32_e32 v86, v86
	v_cvt_pk_bf16_f32 v177, v250, v251
	v_add_f32_e32 v240, v244, v240
	v_exp_f32_e32 v87, v87
	v_add_f32_e32 v248, v252, v248
	v_exp_f32_e32 v88, v88
	v_cvt_pk_bf16_f32 v182, v244, v245
	v_add_f32_e32 v240, v245, v240
	v_exp_f32_e32 v89, v89
	v_add_f32_e32 v248, v253, v248
	v_exp_f32_e32 v90, v90
	v_cvt_pk_bf16_f32 v178, v252, v253
	v_add_f32_e32 v240, v246, v240
	v_exp_f32_e32 v91, v91
	v_add_f32_e32 v248, v236, v248
	v_exp_f32_e32 v92, v92
	v_cvt_pk_bf16_f32 v183, v246, v247
	v_add_f32_e32 v240, v247, v240
	v_exp_f32_e32 v93, v93
	v_add_f32_e32 v248, v237, v248
	v_exp_f32_e32 v94, v94
	v_cvt_pk_bf16_f32 v179, v236, v237
	v_add_f32_e32 v240, v240, v248
	v_exp_f32_e32 v95, v95
	v_cvt_pk_bf16_f32 v172, v80, v81
	v_cvt_pk_bf16_f32 v168, v88, v89
	v_add_f32_e32 v80, v80, v81
	v_add_f32_e32 v88, v88, v89
	v_add_f32_e32 v80, v82, v80
	v_add_f32_e32 v88, v90, v88
	v_cvt_pk_bf16_f32 v173, v82, v83
	v_add_f32_e32 v80, v83, v80
	v_add_f32_e32 v88, v91, v88
	v_cvt_pk_bf16_f32 v169, v90, v91
	v_add_f32_e32 v80, v84, v80
	v_add_f32_e32 v88, v92, v88
	v_cvt_pk_bf16_f32 v174, v84, v85
	v_add_f32_e32 v80, v85, v80
	v_add_f32_e32 v88, v93, v88
	v_cvt_pk_bf16_f32 v170, v92, v93
	v_add_f32_e32 v80, v86, v80
	v_add_f32_e32 v88, v94, v88
	v_cvt_pk_bf16_f32 v175, v86, v87
	v_add_f32_e32 v80, v87, v80
	v_add_f32_e32 v88, v95, v88
	v_cvt_pk_bf16_f32 v171, v94, v95
	v_add_f32_e32 v80, v80, v88
	v_add_f32_e32 v185, v80, v240
	s_waitcnt vmcnt(3)
	s_cmpk_gt_u32 s64, 0x81
	s_cbranch_scc1 .LBB0_1195
	s_add_i32 s0, s51, 0x8000
	s_and_b32 s0, s0, 0x8000
	s_add_i32 s0, s0, 0
	v_add_u32_e32 v80, s0, v210
	s_waitcnt vmcnt(5)
	ds_write_b128 v80, v[132:135]
	v_add_u32_e32 v80, s0, v211
	s_waitcnt vmcnt(4)
	ds_write_b128 v80, v[128:131]
	v_add_u32_e32 v80, s99, v212
	s_waitcnt vmcnt(3)
	ds_write_b128 v80, v[136:139]
; __device__ __forceinline__ float max3f(float a, float b, float c) { return __builtin_fmaxf(__builtin_fmaxf(a, b), c); }
; __device__ __forceinline__ void rowmax_adjust(f32x16& p0, f32x16& p1, float& m2, f32x16& negm, float& alpha, const bool first) {
;     constexpr float THR2 = THR * 1.4426950408889634f;
;     float pmax = max3f(p0[0], p0[1], p0[2]);
; #pragma unroll
;     for (int r = 3; r < 15; r += 2) pmax = max3f(pmax, p0[r], p0[r + 1]);
;     pmax = max3f(pmax, p0[15], p1[0]);
; #pragma unroll
;     for (int r = 1; r < 15; r += 2) pmax = max3f(pmax, p1[r], p1[r + 1]);
;     pmax = fmaxf(pmax, p1[15]);
;     { auto rr = __builtin_amdgcn_permlane32_swap(__float_as_uint(pmax), __float_as_uint(pmax), false, false);
;       pmax = fmaxf(__uint_as_float(rr[0]), __uint_as_float(rr[1])); }
;     if (!first && __builtin_expect(__all(pmax <= THR2), 1)) { alpha = 1.f; }
.LBB0_1195:
	s_min_u32 s0, s64, 0x7f
	s_lshl_b32 s0, s0, 16
	s_add_i32 s16, s0, 0x40000
	s_add_u32 s0, s58, s16
	s_addc_u32 s1, s59, 0
	global_load_dwordx4 v[132:135], v200, s[0:1]
	global_load_dwordx4 v[128:131], v202, s[0:1]
	v_lshl_add_u64 v[80:81], v[204:205], 0, s[16:17]
	global_load_dwordx4 v[136:139], v[80:81], off
	s_waitcnt lgkmcnt(0)
	s_barrier
	s_add_i32 s99, s98, 0x2400
	s_cmp_eq_u32 s99, 0x6c00
	s_cselect_b32 s99, 0, s99
	v_add_u32_e32 v84, s99, v218
	s_and_b32 s0, s51, 0x8000
	v_add_u32_e32 v187, s0, v217
	ds_read_b128 v[80:83], v84
	ds_read_b128 v[192:195], v84 offset:4608
	ds_read_b128 v[188:191], v84 offset:32
	ds_read_b128 v[196:199], v84 offset:4640
	ds_read_b128 v[220:223], v84 offset:64
	ds_read_b128 v[228:231], v84 offset:4672
	ds_read_b128 v[224:227], v84 offset:96
	ds_read_b128 v[232:235], v84 offset:4704
	ds_read_b64_tr_b16 v[164:165], v187 offset:0
	ds_read_b64_tr_b16 v[166:167], v187 offset:0x800
	ds_read_b64_tr_b16 v[160:161], v187 offset:0x1000
	ds_read_b64_tr_b16 v[162:163], v187 offset:0x1800
	ds_read_b64_tr_b16 v[156:157], v187 offset:0x2000
	ds_read_b64_tr_b16 v[158:159], v187 offset:0x2800
	ds_read_b64_tr_b16 v[152:153], v187 offset:0x3000
	ds_read_b64_tr_b16 v[154:155], v187 offset:0x3800
	s_waitcnt lgkmcnt(15)
	v_mfma_f32_32x32x16_bf16 v[96:111], v[80:83], v[112:115], v[64:79]
	s_waitcnt lgkmcnt(14)
	v_mfma_f32_32x32x16_bf16 v[80:95], v[192:195], v[112:115], v[64:79]
	s_waitcnt lgkmcnt(13)
	v_mfma_f32_32x32x16_bf16 v[96:111], v[188:191], v[116:119], v[96:111]
	s_waitcnt lgkmcnt(12)
	v_mfma_f32_32x32x16_bf16 v[80:95], v[196:199], v[116:119], v[80:95]
	s_waitcnt lgkmcnt(8)
	ds_read_b64_tr_b16 v[188:189], v187 offset:0x200
	ds_read_b64_tr_b16 v[190:191], v187 offset:0xa00
	ds_read_b64_tr_b16 v[192:193], v187 offset:0x1200
	ds_read_b64_tr_b16 v[194:195], v187 offset:0x1a00
	ds_read_b64_tr_b16 v[196:197], v187 offset:0x2200
	ds_read_b64_tr_b16 v[198:199], v187 offset:0x2a00
	ds_read_b64_tr_b16 v[236:237], v187 offset:0x3200
	ds_read_b64_tr_b16 v[238:239], v187 offset:0x3a00
	v_mfma_f32_32x32x16_bf16 v[96:111], v[220:223], v[120:123], v[96:111]
	v_mfma_f32_32x32x16_bf16 v[80:95], v[228:231], v[120:123], v[80:95]
	v_mfma_f32_32x32x16_bf16 v[96:111], v[224:227], v[124:127], v[96:111]
	v_mfma_f32_32x32x16_bf16 v[80:95], v[232:235], v[124:127], v[80:95]
	ds_read_b64_tr_b16 v[220:221], v187 offset:0x600
	ds_read_b64_tr_b16 v[222:223], v187 offset:0xe00
	ds_read_b64_tr_b16 v[224:225], v187 offset:0x1600
	ds_read_b64_tr_b16 v[226:227], v187 offset:0x1e00
	ds_read_b64_tr_b16 v[228:229], v187 offset:0x2600
	ds_read_b64_tr_b16 v[230:231], v187 offset:0x2e00
	ds_read_b64_tr_b16 v[232:233], v187 offset:0x3600
	ds_read_b64_tr_b16 v[234:235], v187 offset:0x3e00
	s_waitcnt lgkmcnt(15)
	v_mfma_f32_32x32x16_bf16 v[48:63], v[180:183], v[164:167], v[48:63]
	v_mfma_f32_32x32x16_bf16 v[48:63], v[176:179], v[160:163], v[48:63]
	v_mfma_f32_32x32x16_bf16 v[48:63], v[172:175], v[156:159], v[48:63]
	v_mfma_f32_32x32x16_bf16 v[48:63], v[168:171], v[152:155], v[48:63]
	ds_read_b64_tr_b16 v[164:165], v187 offset:0x400
	ds_read_b64_tr_b16 v[166:167], v187 offset:0xc00
	ds_read_b64_tr_b16 v[160:161], v187 offset:0x1400
	ds_read_b64_tr_b16 v[162:163], v187 offset:0x1c00
	ds_read_b64_tr_b16 v[156:157], v187 offset:0x2400
	ds_read_b64_tr_b16 v[158:159], v187 offset:0x2c00
	ds_read_b64_tr_b16 v[152:153], v187 offset:0x3400
	ds_read_b64_tr_b16 v[154:155], v187 offset:0x3c00
	s_waitcnt lgkmcnt(15)
	v_mfma_f32_32x32x16_bf16 v[32:47], v[180:183], v[188:191], v[32:47]
	v_mfma_f32_32x32x16_bf16 v[32:47], v[176:179], v[192:195], v[32:47]
	v_mfma_f32_32x32x16_bf16 v[32:47], v[172:175], v[196:199], v[32:47]
	v_mfma_f32_32x32x16_bf16 v[32:47], v[168:171], v[236:239], v[32:47]
	s_waitcnt lgkmcnt(8)
	v_mfma_f32_32x32x16_bf16 v[0:15], v[180:183], v[220:223], v[0:15]
	v_mfma_f32_32x32x16_bf16 v[0:15], v[176:179], v[224:227], v[0:15]
	v_mfma_f32_32x32x16_bf16 v[0:15], v[172:175], v[228:231], v[0:15]
	v_mfma_f32_32x32x16_bf16 v[0:15], v[168:171], v[232:235], v[0:15]
	s_waitcnt lgkmcnt(0)
	v_mfma_f32_32x32x16_bf16 v[16:31], v[180:183], v[164:167], v[16:31]
	v_mfma_f32_32x32x16_bf16 v[16:31], v[176:179], v[160:163], v[16:31]
	v_mfma_f32_32x32x16_bf16 v[16:31], v[172:175], v[156:159], v[16:31]
	v_mfma_f32_32x32x16_bf16 v[16:31], v[168:171], v[152:155], v[16:31]
	s_barrier
	v_max3_f32 v168, v96, v97, v98
	v_exp_f32_e32 v240, v96
	v_max3_f32 v169, v81, v82, v83
	v_exp_f32_e32 v241, v97
	v_max3_f32 v168, v168, v99, v100
	v_exp_f32_e32 v242, v98
	v_max3_f32 v169, v169, v84, v85
	v_exp_f32_e32 v243, v99
	v_max3_f32 v168, v168, v101, v102
	v_exp_f32_e32 v244, v100
	v_max3_f32 v169, v169, v86, v87
	v_exp_f32_e32 v245, v101
	v_max3_f32 v168, v168, v103, v104
	v_exp_f32_e32 v246, v102
	v_max3_f32 v169, v169, v88, v89
	v_exp_f32_e32 v247, v103
	v_max3_f32 v168, v168, v105, v106
	v_exp_f32_e32 v248, v104
	v_max3_f32 v169, v169, v90, v91
	v_exp_f32_e32 v249, v105
	v_max3_f32 v168, v168, v107, v108
	v_exp_f32_e32 v250, v106
	v_max3_f32 v169, v169, v92, v93
	v_exp_f32_e32 v251, v107
	v_max3_f32 v168, v168, v109, v110
	v_exp_f32_e32 v252, v108
	v_max3_f32 v169, v169, v94, v95
	v_exp_f32_e32 v253, v109
	v_max3_f32 v168, v168, v111, v80
	v_exp_f32_e32 v236, v110
	v_max_f32_e32 v168, v168, v169
	v_exp_f32_e32 v237, v111
	v_mov_b32_e32 v169, v168
	s_nop 1
	v_permlane32_swap_b32_e32 v168, v169
	v_max_f32_e32 v168, v168, v169
	v_cmp_ge_f32_e32 vcc, s83, v168
	v_mov_b32_e32 v187, 1.0
	s_cmp_eq_u64 vcc, exec
	s_cbranch_scc1 .Lsp_do31
	s_branch .LBB0_1202

; #define SBAR() __builtin_amdgcn_sched_barrier(0)
; #define PK4(P, BASE, OUT) do { u32x4 w = {cvtpk_a(P[BASE + 0], P[BASE + 1]), cvtpk_a(P[BASE + 2], P[BASE + 3]), cvtpk_a(P[BASE + 4], P[BASE + 5]), cvtpk_a(P[BASE + 6], P[BASE + 7])}; \
;     OUT = *reinterpret_cast<bf16x8*>(&w); } while (0)
; #define SWAIT() asm volatile("s_waitcnt vmcnt(3)" ::: "memory")
; __device__ __forceinline__ float exp_pack(f32x16& p0, f32x16& p1, bf16x8& pa0, bf16x8& pa1, bf16x8& pa2, bf16x8& pa3) {
; #pragma unroll
;     for (int r = 0; r < 16; ++r) p0[r] = __builtin_amdgcn_exp2f(p0[r]);
; #pragma unroll
;     for (int r = 0; r < 16; ++r) p1[r] = __builtin_amdgcn_exp2f(p1[r]);
;     SBAR(); asm volatile("s_nop 1" ::: "memory"); SBAR();
;     ...
;     PK4(p0, 0, pa0); PK4(p0, 8, pa1); PK4(p1, 0, pa2); PK4(p1, 8, pa3);
;     ...
;     float ps0 = p0[0], ps1 = p1[0];
; #pragma unroll
;     for (int r = 1; r < 16; ++r) { ps0 += p0[r]; ps1 += p1[r]; }
;     float ps = ps0 + ps1;
;     { auto rr = __builtin_amdgcn_permlane32_swap(__float_as_uint(ps), __float_as_uint(ps), false, false);
;       ps = __uint_as_float(rr[0]) + __uint_as_float(rr[1]); }
;     return ps;
; template <bool MLA>
; __device__ __forceinline__ void attn_core(const bf16_t* __restrict__ Qb, const bf16_t* __restrict__ Kh, const bf16_t* __restrict__ Vh, int seq, char* lds,
;                                           f32x16 (&o)[Cfg<MLA>::NCB], const int wid  , const int g  ) {
;     ...
;         SWAIT(); if (j + 3 < NT) SWRITE(((j + 3) % 3) * SHM_K, ((j + 3) & 3) * SHM_V, SO);
.Lsp_do31:
	v_exp_f32_e32 v80, v80
	v_cvt_pk_bf16_f32 v180, v240, v241
	v_cvt_pk_bf16_f32 v176, v248, v249
	v_exp_f32_e32 v81, v81
	v_add_f32_e32 v240, v240, v241
	v_exp_f32_e32 v82, v82
	v_add_f32_e32 v248, v248, v249
	v_add_f32_e32 v240, v242, v240
	v_exp_f32_e32 v83, v83
	v_add_f32_e32 v248, v250, v248
	v_exp_f32_e32 v84, v84
	v_cvt_pk_bf16_f32 v181, v242, v243
	v_add_f32_e32 v240, v243, v240
	v_exp_f32_e32 v85, v85
	v_add_f32_e32 v248, v251, v248
	v_exp_f32_e32 v86, v86
	v_cvt_pk_bf16_f32 v177, v250, v251
	v_add_f32_e32 v240, v244, v240
	v_exp_f32_e32 v87, v87
	v_add_f32_e32 v248, v252, v248
	v_exp_f32_e32 v88, v88
	v_cvt_pk_bf16_f32 v182, v244, v245
	v_add_f32_e32 v240, v245, v240
	v_exp_f32_e32 v89, v89
	v_add_f32_e32 v248, v253, v248
	v_exp_f32_e32 v90, v90
	v_cvt_pk_bf16_f32 v178, v252, v253
	v_add_f32_e32 v240, v246, v240
	v_exp_f32_e32 v91, v91
	v_add_f32_e32 v248, v236, v248
	v_exp_f32_e32 v92, v92
	v_cvt_pk_bf16_f32 v183, v246, v247
	v_add_f32_e32 v240, v247, v240
	v_exp_f32_e32 v93, v93
	v_add_f32_e32 v248, v237, v248
	v_exp_f32_e32 v94, v94
	v_cvt_pk_bf16_f32 v179, v236, v237
	v_add_f32_e32 v240, v240, v248
	v_exp_f32_e32 v95, v95
	v_cvt_pk_bf16_f32 v172, v80, v81
	v_cvt_pk_bf16_f32 v168, v88, v89
	v_add_f32_e32 v80, v80, v81
	v_add_f32_e32 v88, v88, v89
	v_add_f32_e32 v80, v82, v80
	v_add_f32_e32 v88, v90, v88
	v_cvt_pk_bf16_f32 v173, v82, v83
	v_add_f32_e32 v80, v83, v80
	v_add_f32_e32 v88, v91, v88
	v_cvt_pk_bf16_f32 v169, v90, v91
	v_add_f32_e32 v80, v84, v80
	v_add_f32_e32 v88, v92, v88
	v_cvt_pk_bf16_f32 v174, v84, v85
	v_add_f32_e32 v80, v85, v80
	v_add_f32_e32 v88, v93, v88
	v_cvt_pk_bf16_f32 v170, v92, v93
	v_add_f32_e32 v80, v86, v80
	v_add_f32_e32 v88, v94, v88
	v_cvt_pk_bf16_f32 v175, v86, v87
	v_add_f32_e32 v80, v87, v80
	v_add_f32_e32 v88, v95, v88
	v_cvt_pk_bf16_f32 v171, v94, v95
	v_add_f32_e32 v80, v80, v88
	v_add_f32_e32 v80, v80, v240
	s_waitcnt vmcnt(3)
	s_cmpk_gt_u32 s64, 0x80
	s_cbranch_scc1 .LBB0_1180
	s_add_i32 s0, s65, 0
	v_add_u32_e32 v82, s0, v210
	s_waitcnt vmcnt(5)
	ds_write_b128 v82, v[140:143]
	v_add_u32_e32 v82, s0, v211
	s_waitcnt vmcnt(4)
	ds_write_b128 v82, v[144:147]
	v_add_u32_e32 v82, s98, v212
	s_waitcnt vmcnt(3)
	ds_write_b128 v82, v[148:151]
	s_branch .LBB0_1180

; #define SBAR() __builtin_amdgcn_sched_barrier(0)
; #define SWAIT() asm volatile("s_waitcnt vmcnt(3)" ::: "memory")
; #define VSEG(j) do { rowmax_adjust(S0, S1, m2, negm, alpha, (j) == 0); RESC(alpha); l_reg = l_reg * alpha + exp_pack(S0, S1, pa0, pa1, pa2, pa3); } while (0)
; template <bool MLA>
; __device__ __forceinline__ void attn_core(const bf16_t* __restrict__ Qb, const bf16_t* __restrict__ Kh, const bf16_t* __restrict__ Vh, int seq, char* lds,
;                                           f32x16 (&o)[Cfg<MLA>::NCB], const int wid  , const int g  ) {
;     ...
;     SLOAD(SE, 0); SLOAD(SO, 64); asm volatile("s_waitcnt vmcnt(0)" ::: "memory");
;     SWRITE(0, 0, SE); SWRITE(SHM_K, SHM_V, SO);
;     SLOAD(SE, 2 * 64); SLOAD(SO, 3 * 64);
;     __syncthreads();
;     { int g_ = g; asm volatile("" : "+s"(g_)); if (g_ == 1) __syncthreads(); }
;     for (int j = 0; j < NT; j += 2) {
;         SBAR(); MSEG(j); SBAR();
;         __syncthreads();
;         SBAR(); VSEG(j);
;         SWAIT(); if (j + 2 < NT) SWRITE(((j + 2) % 3) * SHM_K, ((j + 2) & 3) * SHM_V, SE);
;         if (!(MLA && PROBE_NOLOAD)) { const int tn = (j + 4 < NT) ? j + 4 : NT - 1; SLOAD(SE, tn * 64); } SBAR();
.LBB0_1226:
	v_add_f32_e32 v157, v48, v49
	s_add_u32 s10, s58, 0x78000
	v_add_co_u32_e32 v48, vcc, 0x50000, v148
	s_addc_u32 s11, s59, 0
	s_nop 0
	v_addc_co_u32_e32 v49, vcc, 0, v149, vcc
	global_load_dwordx4 v[116:119], v[48:49], off
	global_load_dwordx4 v[124:127], v146, s[10:11]
	global_load_dwordx4 v[120:123], v200, s[10:11]
	v_add_f32_e32 v50, v159, v160
	v_add_f32_e32 v50, 0, v50
	v_fmac_f32_e32 v157, v50, v161
	v_mul_f32_e32 v157, 0.5, v157
	s_mov_b32 s51, 5
	s_mov_b32 s60, 0xa000
	s_mov_b32 s99, 0x4400
	s_waitcnt lgkmcnt(0)
	s_barrier
	s_branch .LBB0_1228

; __device__ __forceinline__ float max3f(float a, float b, float c) { return __builtin_fmaxf(__builtin_fmaxf(a, b), c); }
; __device__ __forceinline__ void rowmax_adjust(f32x16& p0, f32x16& p1, float& m2, f32x16& negm, float& alpha, const bool first) {
;     constexpr float THR2 = THR * 1.4426950408889634f;
;     float pmax = max3f(p0[0], p0[1], p0[2]);
; #pragma unroll
;     for (int r = 3; r < 15; r += 2) pmax = max3f(pmax, p0[r], p0[r + 1]);
;     pmax = max3f(pmax, p0[15], p1[0]);
; #pragma unroll
;     for (int r = 1; r < 15; r += 2) pmax = max3f(pmax, p1[r], p1[r + 1]);
;     pmax = fmaxf(pmax, p1[15]);
;     { auto rr = __builtin_amdgcn_permlane32_swap(__float_as_uint(pmax), __float_as_uint(pmax), false, false);
;       pmax = fmaxf(__uint_as_float(rr[0]), __uint_as_float(rr[1])); }
;     if (!first && __builtin_expect(__all(pmax <= THR2), 1)) { alpha = 1.f; }
.LBB0_1228:
	s_add_i32 s61, s51, -3
	s_add_i32 s98, s99, 0x4400
	s_cmp_eq_u32 s98, 0xcc00
	s_cselect_b32 s98, 0, s98
	v_add_u32_e32 v52, s98, v152
	ds_read_b128 v[48:51], v52 offset:32768
	ds_read_b128 v[158:161], v52 offset:32800
	ds_read_b128 v[162:165], v52 offset:41472
	ds_read_b128 v[166:169], v52 offset:41504
	ds_read_b128 v[170:173], v52 offset:32832
	ds_read_b128 v[174:177], v52 offset:32864
	ds_read_b128 v[178:181], v52 offset:41536
	ds_read_b128 v[182:185], v52 offset:41568
	ds_read_b128 v[186:189], v52 offset:32896
	ds_read_b128 v[190:193], v52 offset:32928
	ds_read_b128 v[194:197], v52 offset:41600
	ds_read_b128 v[202:205], v52 offset:41632
	s_waitcnt lgkmcnt(11)
	v_mfma_f32_32x32x16_bf16 v[64:79], v[48:51], v[80:83], v[32:47]
	s_waitcnt lgkmcnt(9)
	v_mfma_f32_32x32x16_bf16 v[48:63], v[162:165], v[80:83], v[32:47]
	v_mfma_f32_32x32x16_bf16 v[64:79], v[158:161], v[84:87], v[64:79]
	s_waitcnt lgkmcnt(8)
	v_mfma_f32_32x32x16_bf16 v[48:63], v[166:169], v[84:87], v[48:63]
	s_waitcnt lgkmcnt(7)
	v_mfma_f32_32x32x16_bf16 v[64:79], v[170:173], v[88:91], v[64:79]
	s_waitcnt lgkmcnt(5)
	v_mfma_f32_32x32x16_bf16 v[48:63], v[178:181], v[88:91], v[48:63]
	s_waitcnt lgkmcnt(4)
	s_waitcnt lgkmcnt(3)
	s_waitcnt lgkmcnt(1)
	s_waitcnt lgkmcnt(0)
	s_and_b32 s62, s60, 0x6000
	v_add_u32_e32 v198, s62, v155
	ds_read_b64_tr_b16 v[158:159], v198 offset:0
	ds_read_b64_tr_b16 v[160:161], v198 offset:0x400
	ds_read_b64_tr_b16 v[162:163], v198 offset:0x800
	ds_read_b64_tr_b16 v[164:165], v198 offset:0xc00
	ds_read_b64_tr_b16 v[166:167], v198 offset:0x1000
	ds_read_b64_tr_b16 v[168:169], v198 offset:0x1400
	ds_read_b64_tr_b16 v[170:171], v198 offset:0x1800
	ds_read_b64_tr_b16 v[172:173], v198 offset:0x1c00
	ds_read_b64_tr_b16 v[178:179], v198 offset:0x200
	ds_read_b64_tr_b16 v[180:181], v198 offset:0x600
	ds_read_b64_tr_b16 v[210:211], v198 offset:0xa00
	ds_read_b64_tr_b16 v[212:213], v198 offset:0xe00
	ds_read_b64_tr_b16 v[214:215], v198 offset:0x1200
	ds_read_b64_tr_b16 v[216:217], v198 offset:0x1600
	ds_read_b64_tr_b16 v[218:219], v198 offset:0x1a00
	ds_read_b64_tr_b16 v[220:221], v198 offset:0x1e00
	s_nop 0
	v_mfma_f32_32x32x16_bf16 v[64:79], v[174:177], v[92:95], v[64:79]
	v_mfma_f32_32x32x16_bf16 v[48:63], v[182:185], v[92:95], v[48:63]
	v_mfma_f32_32x32x16_bf16 v[64:79], v[186:189], v[96:99], v[64:79]
	v_mfma_f32_32x32x16_bf16 v[48:63], v[194:197], v[96:99], v[48:63]
	v_mfma_f32_32x32x16_bf16 v[64:79], v[190:193], v[100:103], v[64:79]
	v_mfma_f32_32x32x16_bf16 v[48:63], v[202:205], v[100:103], v[48:63]
	s_waitcnt lgkmcnt(0)
	v_mfma_f32_32x32x16_bf16 v[0:15], v[140:143], v[158:161], v[0:15]
	v_mfma_f32_32x32x16_bf16 v[16:31], v[140:143], v[178:181], v[16:31]
	v_mfma_f32_32x32x16_bf16 v[0:15], v[136:139], v[162:165], v[0:15]
	v_mfma_f32_32x32x16_bf16 v[16:31], v[136:139], v[210:213], v[16:31]
	v_mfma_f32_32x32x16_bf16 v[0:15], v[132:135], v[166:169], v[0:15]
	v_mfma_f32_32x32x16_bf16 v[16:31], v[132:135], v[214:217], v[16:31]
	v_mfma_f32_32x32x16_bf16 v[0:15], v[128:131], v[170:173], v[0:15]
	v_mfma_f32_32x32x16_bf16 v[16:31], v[128:131], v[218:221], v[16:31]
	s_barrier
	s_nop 1
	v_max3_f32 v128, v64, v65, v66
	v_exp_f32_e32 v226, v64
	v_max3_f32 v129, v49, v50, v51
	v_exp_f32_e32 v227, v65
	v_max3_f32 v128, v128, v67, v68
	v_exp_f32_e32 v228, v66
	v_max3_f32 v129, v129, v52, v53
	v_exp_f32_e32 v229, v67
	v_max3_f32 v128, v128, v69, v70
	v_exp_f32_e32 v230, v68
	v_max3_f32 v129, v129, v54, v55
	v_exp_f32_e32 v231, v69
	v_max3_f32 v128, v128, v71, v72
	v_exp_f32_e32 v232, v70
	v_max3_f32 v129, v129, v56, v57
	v_exp_f32_e32 v233, v71
	v_max3_f32 v128, v128, v73, v74
	v_exp_f32_e32 v234, v72
	v_max3_f32 v129, v129, v58, v59
	v_exp_f32_e32 v235, v73
	v_max3_f32 v128, v128, v75, v76
	v_exp_f32_e32 v236, v74
	v_max3_f32 v129, v129, v60, v61
	v_exp_f32_e32 v237, v75
	v_max3_f32 v128, v128, v77, v78
	v_exp_f32_e32 v238, v76
	v_max3_f32 v129, v129, v62, v63
	v_exp_f32_e32 v239, v77
	v_max3_f32 v128, v128, v79, v48
	v_exp_f32_e32 v240, v78
	v_max_f32_e32 v128, v128, v129
	v_exp_f32_e32 v241, v79
	v_mov_b32_e32 v129, v128
	s_nop 1
	v_permlane32_swap_b32_e32 v128, v129
	v_max_f32_e32 v128, v128, v129
	v_cmp_ge_f32_e32 vcc, s83, v128
	v_mov_b32_e32 v158, 1.0
	s_cmp_eq_u64 vcc, exec
	s_cbranch_scc1 .Lsp_me
	s_branch .LBB0_1244

; #define SBAR() __builtin_amdgcn_sched_barrier(0)
; #define PK4(P, BASE, OUT) do { u32x4 w = {cvtpk_a(P[BASE + 0], P[BASE + 1]), cvtpk_a(P[BASE + 2], P[BASE + 3]), cvtpk_a(P[BASE + 4], P[BASE + 5]), cvtpk_a(P[BASE + 6], P[BASE + 7])}; \
;     OUT = *reinterpret_cast<bf16x8*>(&w); } while (0)
; #define SWAIT() asm volatile("s_waitcnt vmcnt(3)" ::: "memory")
; __device__ __forceinline__ float exp_pack(f32x16& p0, f32x16& p1, bf16x8& pa0, bf16x8& pa1, bf16x8& pa2, bf16x8& pa3) {
; #pragma unroll
;     for (int r = 0; r < 16; ++r) p0[r] = __builtin_amdgcn_exp2f(p0[r]);
; #pragma unroll
;     for (int r = 0; r < 16; ++r) p1[r] = __builtin_amdgcn_exp2f(p1[r]);
;     SBAR(); asm volatile("s_nop 1" ::: "memory"); SBAR();
;     ...
;     PK4(p0, 0, pa0); PK4(p0, 8, pa1); PK4(p1, 0, pa2); PK4(p1, 8, pa3);
;     ...
;     float ps0 = p0[0], ps1 = p1[0];
; #pragma unroll
;     for (int r = 1; r < 16; ++r) { ps0 += p0[r]; ps1 += p1[r]; }
;     float ps = ps0 + ps1;
;     { auto rr = __builtin_amdgcn_permlane32_swap(__float_as_uint(ps), __float_as_uint(ps), false, false);
;       ps = __uint_as_float(rr[0]) + __uint_as_float(rr[1]); }
;     return ps;
; }
; template <bool MLA>
; __device__ __forceinline__ void attn_core(const bf16_t* __restrict__ Qb, const bf16_t* __restrict__ Kh, const bf16_t* __restrict__ Vh, int seq, char* lds,
;                                           f32x16 (&o)[Cfg<MLA>::NCB], const int wid  , const int g  ) {
;     ...
;     __syncthreads();
;     SLOAD(SE, 0); SLOAD(SO, 64); asm volatile("s_waitcnt vmcnt(0)" ::: "memory");
;     SWRITE(0, 0, SE); SWRITE(SHM_K, SHM_V, SO);
;     SLOAD(SE, 2 * 64); SLOAD(SO, 3 * 64);
;     __syncthreads();
;     { int g_ = g; asm volatile("" : "+s"(g_)); if (g_ == 1) __syncthreads(); }
;     for (int j = 0; j < NT; j += 2) {
;         SBAR(); MSEG(j); SBAR();
;         __syncthreads();
;         SBAR(); VSEG(j);
;         SWAIT(); if (j + 2 < NT) SWRITE(((j + 2) % 3) * SHM_K, ((j + 2) & 3) * SHM_V, SE);
;         if (!(MLA && PROBE_NOLOAD)) { const int tn = (j + 4 < NT) ? j + 4 : NT - 1; SLOAD(SE, tn * 64); } SBAR();
;         __syncthreads();
;         SBAR(); MSEG(j + 1); SBAR();
;         __syncthreads();
;         SBAR(); VSEG(j + 1);
;         SWAIT(); if (j + 3 < NT) SWRITE(((j + 3) % 3) * SHM_K, ((j + 3) & 3) * SHM_V, SO);
.Lsp_me:
	v_exp_f32_e32 v48, v48
	v_cvt_pk_bf16_f32 v140, v226, v227
	v_cvt_pk_bf16_f32 v136, v234, v235
	v_exp_f32_e32 v49, v49
	v_add_f32_e32 v226, v226, v227
	v_exp_f32_e32 v50, v50
	v_add_f32_e32 v234, v234, v235
	v_add_f32_e32 v226, v228, v226
	v_exp_f32_e32 v51, v51
	v_add_f32_e32 v234, v236, v234
	v_exp_f32_e32 v52, v52
	v_cvt_pk_bf16_f32 v141, v228, v229
	v_add_f32_e32 v226, v229, v226
	v_exp_f32_e32 v53, v53
	v_add_f32_e32 v234, v237, v234
	v_exp_f32_e32 v54, v54
	v_cvt_pk_bf16_f32 v137, v236, v237
	v_add_f32_e32 v226, v230, v226
	v_exp_f32_e32 v55, v55
	v_add_f32_e32 v234, v238, v234
	v_exp_f32_e32 v56, v56
	v_cvt_pk_bf16_f32 v142, v230, v231
	v_add_f32_e32 v226, v231, v226
	v_exp_f32_e32 v57, v57
	v_add_f32_e32 v234, v239, v234
	v_exp_f32_e32 v58, v58
	v_cvt_pk_bf16_f32 v138, v238, v239
	v_add_f32_e32 v226, v232, v226
	v_exp_f32_e32 v59, v59
	v_add_f32_e32 v234, v240, v234
	v_exp_f32_e32 v60, v60
	v_cvt_pk_bf16_f32 v143, v232, v233
	v_add_f32_e32 v226, v233, v226
	v_exp_f32_e32 v61, v61
	v_add_f32_e32 v234, v241, v234
	v_exp_f32_e32 v62, v62
	v_cvt_pk_bf16_f32 v139, v240, v241
	v_add_f32_e32 v226, v226, v234
	v_exp_f32_e32 v63, v63
	v_cvt_pk_bf16_f32 v132, v48, v49
	v_cvt_pk_bf16_f32 v128, v56, v57
	v_add_f32_e32 v48, v48, v49
	v_add_f32_e32 v56, v56, v57
	v_add_f32_e32 v48, v50, v48
	v_add_f32_e32 v56, v58, v56
	v_cvt_pk_bf16_f32 v133, v50, v51
	v_add_f32_e32 v48, v51, v48
	v_add_f32_e32 v56, v59, v56
	v_cvt_pk_bf16_f32 v129, v58, v59
	v_add_f32_e32 v48, v52, v48
	v_add_f32_e32 v56, v60, v56
	v_cvt_pk_bf16_f32 v134, v52, v53
	v_add_f32_e32 v48, v53, v48
	v_add_f32_e32 v56, v61, v56
	v_cvt_pk_bf16_f32 v130, v60, v61
	v_add_f32_e32 v48, v54, v48
	v_add_f32_e32 v56, v62, v56
	v_cvt_pk_bf16_f32 v135, v54, v55
	v_add_f32_e32 v48, v55, v48
	v_add_f32_e32 v56, v63, v56
	v_cvt_pk_bf16_f32 v131, v62, v63
	v_add_f32_e32 v48, v48, v56
	v_add_f32_e32 v159, v48, v226
	s_waitcnt vmcnt(3)
	s_cmpk_gt_u32 s61, 0x81
	s_cbranch_scc1 .LBB0_1236
	s_add_i32 s10, s60, 0xffffe000
	s_and_b32 s10, s10, 0x4000
	v_add_u32_e32 v48, s10, v145
	s_waitcnt vmcnt(5)
	ds_write_b128 v48, v[112:115]
	v_add_u32_e32 v48, s99, v144
	s_and_b64 vcc, exec, s[4:5]
	s_waitcnt vmcnt(4)
	ds_write_b128 v48, v[108:111] offset:32768
	s_cbranch_vccnz .LBB0_1236
	v_add_u32_e32 v48, s99, v150
	s_waitcnt vmcnt(3)
	ds_write_b128 v48, v[104:107] offset:32768
.LBB0_1236:
	s_min_u32 s10, s61, 0x7f
	s_lshl_b32 s10, s10, 6
	s_add_i32 s16, s10, 0x100
	s_add_i32 s38, s60, 0xffffa000
	s_mul_i32 s10, s16, 0x600
	s_add_u32 s10, s58, s10
	s_addc_u32 s11, s59, 0
	s_lshl_b32 s16, s16, 10
	v_lshl_add_u64 v[48:49], v[148:149], 0, s[16:17]
	global_load_dwordx4 v[112:115], v[48:49], off
	global_load_dwordx4 v[108:111], v146, s[10:11]
	global_load_dwordx4 v[104:107], v200, s[10:11]
	s_waitcnt lgkmcnt(0)
	s_barrier
	s_add_i32 s99, s98, 0x4400
	s_cmp_eq_u32 s99, 0xcc00
	s_cselect_b32 s99, 0, s99
	v_add_u32_e32 v52, s99, v152
	ds_read_b128 v[48:51], v52 offset:32768
	ds_read_b128 v[162:165], v52 offset:32800
	ds_read_b128 v[166:169], v52 offset:41472
	ds_read_b128 v[170:173], v52 offset:41504
	ds_read_b128 v[174:177], v52 offset:32832
	ds_read_b128 v[178:181], v52 offset:32864
	ds_read_b128 v[182:185], v52 offset:41536
	ds_read_b128 v[186:189], v52 offset:41568
	ds_read_b128 v[190:193], v52 offset:32896
	ds_read_b128 v[194:197], v52 offset:32928
	ds_read_b128 v[202:205], v52 offset:41600
	ds_read_b128 v[210:213], v52 offset:41632
	s_and_b32 s10, s38, 0x4000
	s_waitcnt lgkmcnt(11)
	v_mfma_f32_32x32x16_bf16 v[64:79], v[48:51], v[80:83], v[32:47]
	s_waitcnt lgkmcnt(9)
	v_mfma_f32_32x32x16_bf16 v[48:63], v[166:169], v[80:83], v[32:47]
	v_mfma_f32_32x32x16_bf16 v[64:79], v[162:165], v[84:87], v[64:79]
	s_waitcnt lgkmcnt(8)
	v_mfma_f32_32x32x16_bf16 v[48:63], v[170:173], v[84:87], v[48:63]
	s_waitcnt lgkmcnt(7)
	v_mfma_f32_32x32x16_bf16 v[64:79], v[174:177], v[88:91], v[64:79]
	s_waitcnt lgkmcnt(5)
	v_mfma_f32_32x32x16_bf16 v[48:63], v[182:185], v[88:91], v[48:63]
	v_add_u32_e32 v161, s10, v155
	s_waitcnt lgkmcnt(4)
	s_waitcnt lgkmcnt(3)
	s_waitcnt lgkmcnt(1)
	s_waitcnt lgkmcnt(0)
	ds_read_b64_tr_b16 v[162:163], v161 offset:0
	ds_read_b64_tr_b16 v[164:165], v161 offset:0x400
	ds_read_b64_tr_b16 v[166:167], v161 offset:0x800
	ds_read_b64_tr_b16 v[168:169], v161 offset:0xc00
	ds_read_b64_tr_b16 v[170:171], v161 offset:0x1000
	ds_read_b64_tr_b16 v[172:173], v161 offset:0x1400
	ds_read_b64_tr_b16 v[174:175], v161 offset:0x1800
	ds_read_b64_tr_b16 v[176:177], v161 offset:0x1c00
	ds_read_b64_tr_b16 v[182:183], v161 offset:0x200
	ds_read_b64_tr_b16 v[184:185], v161 offset:0x600
	ds_read_b64_tr_b16 v[214:215], v161 offset:0xa00
	ds_read_b64_tr_b16 v[216:217], v161 offset:0xe00
	ds_read_b64_tr_b16 v[218:219], v161 offset:0x1200
	ds_read_b64_tr_b16 v[220:221], v161 offset:0x1600
	ds_read_b64_tr_b16 v[222:223], v161 offset:0x1a00
	ds_read_b64_tr_b16 v[224:225], v161 offset:0x1e00
	s_nop 0
	v_mfma_f32_32x32x16_bf16 v[64:79], v[178:181], v[92:95], v[64:79]
	v_mfma_f32_32x32x16_bf16 v[48:63], v[186:189], v[92:95], v[48:63]
	v_mfma_f32_32x32x16_bf16 v[64:79], v[190:193], v[96:99], v[64:79]
	v_mfma_f32_32x32x16_bf16 v[48:63], v[202:205], v[96:99], v[48:63]
	v_mfma_f32_32x32x16_bf16 v[64:79], v[194:197], v[100:103], v[64:79]
	v_mfma_f32_32x32x16_bf16 v[48:63], v[210:213], v[100:103], v[48:63]
	s_waitcnt lgkmcnt(0)
	v_mfma_f32_32x32x16_bf16 v[0:15], v[140:143], v[162:165], v[0:15]
	v_mfma_f32_32x32x16_bf16 v[16:31], v[140:143], v[182:185], v[16:31]
	v_mfma_f32_32x32x16_bf16 v[0:15], v[136:139], v[166:169], v[0:15]
	v_mfma_f32_32x32x16_bf16 v[16:31], v[136:139], v[214:217], v[16:31]
	v_mfma_f32_32x32x16_bf16 v[0:15], v[132:135], v[170:173], v[0:15]
	v_mfma_f32_32x32x16_bf16 v[16:31], v[132:135], v[218:221], v[16:31]
	v_mfma_f32_32x32x16_bf16 v[0:15], v[128:131], v[174:177], v[0:15]
	v_mfma_f32_32x32x16_bf16 v[16:31], v[128:131], v[222:225], v[16:31]
	s_barrier
	s_nop 1
	v_max3_f32 v128, v64, v65, v66
	v_exp_f32_e32 v226, v64
	v_max3_f32 v129, v49, v50, v51
	v_exp_f32_e32 v227, v65
	v_max3_f32 v128, v128, v67, v68
	v_exp_f32_e32 v228, v66
	v_max3_f32 v129, v129, v52, v53
	v_exp_f32_e32 v229, v67
	v_max3_f32 v128, v128, v69, v70
	v_exp_f32_e32 v230, v68
	v_max3_f32 v129, v129, v54, v55
	v_exp_f32_e32 v231, v69
	v_max3_f32 v128, v128, v71, v72
	v_exp_f32_e32 v232, v70
	v_max3_f32 v129, v129, v56, v57
	v_exp_f32_e32 v233, v71
	v_max3_f32 v128, v128, v73, v74
	v_exp_f32_e32 v234, v72
	v_max3_f32 v129, v129, v58, v59
	v_exp_f32_e32 v235, v73
	v_max3_f32 v128, v128, v75, v76
	v_exp_f32_e32 v236, v74
	v_max3_f32 v129, v129, v60, v61
	v_exp_f32_e32 v237, v75
	v_max3_f32 v128, v128, v77, v78
	v_exp_f32_e32 v238, v76
	v_max3_f32 v129, v129, v62, v63
	v_exp_f32_e32 v239, v77
	v_max3_f32 v128, v128, v79, v48
	v_exp_f32_e32 v240, v78
	v_max_f32_e32 v128, v128, v129
	v_exp_f32_e32 v241, v79
	v_mov_b32_e32 v129, v128
	s_nop 1
	v_permlane32_swap_b32_e32 v128, v129
	v_max_f32_e32 v128, v128, v129
	v_cmp_ge_f32_e32 vcc, s83, v128
	v_mov_b32_e32 v161, 1.0
	s_cmp_eq_u64 vcc, exec
	s_cbranch_scc1 .Lsp_mo
	s_branch .LBB0_1245

; #define SBAR() __builtin_amdgcn_sched_barrier(0)
; #define PK4(P, BASE, OUT) do { u32x4 w = {cvtpk_a(P[BASE + 0], P[BASE + 1]), cvtpk_a(P[BASE + 2], P[BASE + 3]), cvtpk_a(P[BASE + 4], P[BASE + 5]), cvtpk_a(P[BASE + 6], P[BASE + 7])}; \
;     OUT = *reinterpret_cast<bf16x8*>(&w); } while (0)
; #define SWAIT() asm volatile("s_waitcnt vmcnt(3)" ::: "memory")
; #define VSEG(j) do { rowmax_adjust(S0, S1, m2, negm, alpha, (j) == 0); RESC(alpha); l_reg = l_reg * alpha + exp_pack(S0, S1, pa0, pa1, pa2, pa3); } while (0)
; __device__ __forceinline__ float exp_pack(f32x16& p0, f32x16& p1, bf16x8& pa0, bf16x8& pa1, bf16x8& pa2, bf16x8& pa3) {
; #pragma unroll
;     for (int r = 0; r < 16; ++r) p0[r] = __builtin_amdgcn_exp2f(p0[r]);
; #pragma unroll
;     for (int r = 0; r < 16; ++r) p1[r] = __builtin_amdgcn_exp2f(p1[r]);
;     SBAR(); asm volatile("s_nop 1" ::: "memory"); SBAR();
;     ...
;     PK4(p0, 0, pa0); PK4(p0, 8, pa1); PK4(p1, 0, pa2); PK4(p1, 8, pa3);
;     ...
;     float ps0 = p0[0], ps1 = p1[0];
; #pragma unroll
;     for (int r = 1; r < 16; ++r) { ps0 += p0[r]; ps1 += p1[r]; }
;     float ps = ps0 + ps1;
;     { auto rr = __builtin_amdgcn_permlane32_swap(__float_as_uint(ps), __float_as_uint(ps), false, false);
;       ps = __uint_as_float(rr[0]) + __uint_as_float(rr[1]); }
;     return ps;
; }
; template <bool MLA>
; __device__ __forceinline__ void attn_core(const bf16_t* __restrict__ Qb, const bf16_t* __restrict__ Kh, const bf16_t* __restrict__ Vh, int seq, char* lds,
;                                           f32x16 (&o)[Cfg<MLA>::NCB], const int wid  , const int g  ) {
;     ...
;         SWAIT(); if (j + 2 < NT) SWRITE(((j + 2) % 3) * SHM_K, ((j + 2) & 3) * SHM_V, SE);
;         if (!(MLA && PROBE_NOLOAD)) { const int tn = (j + 4 < NT) ? j + 4 : NT - 1; SLOAD(SE, tn * 64); } SBAR();
;         __syncthreads();
;         SBAR(); MSEG(j + 1); SBAR();
;         __syncthreads();
;         SBAR(); VSEG(j + 1);
;         SWAIT(); if (j + 3 < NT) SWRITE(((j + 3) % 3) * SHM_K, ((j + 3) & 3) * SHM_V, SO);
;         if (!(MLA && PROBE_NOLOAD)) { const int tn = (j + 5 < NT) ? j + 5 : NT - 1; SLOAD(SO, tn * 64); } SBAR();
.Lsp_mo:
	v_exp_f32_e32 v48, v48
	v_cvt_pk_bf16_f32 v140, v226, v227
	v_cvt_pk_bf16_f32 v136, v234, v235
	v_exp_f32_e32 v49, v49
	v_add_f32_e32 v226, v226, v227
	v_exp_f32_e32 v50, v50
	v_add_f32_e32 v234, v234, v235
	v_add_f32_e32 v226, v228, v226
	v_exp_f32_e32 v51, v51
	v_add_f32_e32 v234, v236, v234
	v_exp_f32_e32 v52, v52
	v_cvt_pk_bf16_f32 v141, v228, v229
	v_add_f32_e32 v226, v229, v226
	v_exp_f32_e32 v53, v53
	v_add_f32_e32 v234, v237, v234
	v_exp_f32_e32 v54, v54
	v_cvt_pk_bf16_f32 v137, v236, v237
	v_add_f32_e32 v226, v230, v226
	v_exp_f32_e32 v55, v55
	v_add_f32_e32 v234, v238, v234
	v_exp_f32_e32 v56, v56
	v_cvt_pk_bf16_f32 v142, v230, v231
	v_add_f32_e32 v226, v231, v226
	v_exp_f32_e32 v57, v57
	v_add_f32_e32 v234, v239, v234
	v_exp_f32_e32 v58, v58
	v_cvt_pk_bf16_f32 v138, v238, v239
	v_add_f32_e32 v226, v232, v226
	v_exp_f32_e32 v59, v59
	v_add_f32_e32 v234, v240, v234
	v_exp_f32_e32 v60, v60
	v_cvt_pk_bf16_f32 v143, v232, v233
	v_add_f32_e32 v226, v233, v226
	v_exp_f32_e32 v61, v61
	v_add_f32_e32 v234, v241, v234
	v_exp_f32_e32 v62, v62
	v_cvt_pk_bf16_f32 v139, v240, v241
	v_add_f32_e32 v226, v226, v234
	v_exp_f32_e32 v63, v63
	v_cvt_pk_bf16_f32 v132, v48, v49
	v_cvt_pk_bf16_f32 v128, v56, v57
	v_add_f32_e32 v48, v48, v49
	v_add_f32_e32 v56, v56, v57
	v_add_f32_e32 v48, v50, v48
	v_add_f32_e32 v56, v58, v56
	v_cvt_pk_bf16_f32 v133, v50, v51
	v_add_f32_e32 v48, v51, v48
	v_add_f32_e32 v56, v59, v56
	v_cvt_pk_bf16_f32 v129, v58, v59
	v_add_f32_e32 v48, v52, v48
	v_add_f32_e32 v56, v60, v56
	v_cvt_pk_bf16_f32 v134, v52, v53
	v_add_f32_e32 v48, v53, v48
	v_add_f32_e32 v56, v61, v56
	v_cvt_pk_bf16_f32 v130, v60, v61
	v_add_f32_e32 v48, v54, v48
	v_add_f32_e32 v56, v62, v56
	v_cvt_pk_bf16_f32 v135, v54, v55
	v_add_f32_e32 v48, v55, v48
	v_add_f32_e32 v56, v63, v56
	v_cvt_pk_bf16_f32 v131, v62, v63
	v_add_f32_e32 v48, v48, v56
	v_add_f32_e32 v48, v48, v226
	s_waitcnt vmcnt(3)
	s_cmpk_gt_u32 s61, 0x80
	s_cbranch_scc1 .LBB0_1227
	v_add_u32_e32 v50, s62, v145
	s_waitcnt vmcnt(5)
	ds_write_b128 v50, v[116:119]
	v_add_u32_e32 v50, s98, v144
	s_and_b64 vcc, exec, s[4:5]
	s_waitcnt vmcnt(4)
	ds_write_b128 v50, v[124:127] offset:32768
	s_cbranch_vccnz .LBB0_1227
	v_add_u32_e32 v50, s98, v150
	s_waitcnt vmcnt(3)
	ds_write_b128 v50, v[120:123] offset:32768
	s_branch .LBB0_1227

; __global__ void __launch_bounds__(512, 2) fwd_mega(Args a) {
;     extern __shared__ __attribute__((aligned(16))) unsigned char lds[];
;     cg::grid_group grid = cg::this_grid();
;     const int wave = __builtin_amdgcn_readfirstlane((int)threadIdx.x >> 6);
	.amdhsa_kernel _Z8fwd_mega4Args
		.amdhsa_group_segment_fixed_size 0
		.amdhsa_private_segment_fixed_size 0
		.amdhsa_kernarg_size 416
		.amdhsa_user_sgpr_count 2
		.amdhsa_user_sgpr_dispatch_ptr 0
		.amdhsa_user_sgpr_queue_ptr 0
		.amdhsa_user_sgpr_kernarg_segment_ptr 1
		.amdhsa_user_sgpr_dispatch_id 0
		.amdhsa_user_sgpr_kernarg_preload_length 0
		.amdhsa_user_sgpr_kernarg_preload_offset 0
		.amdhsa_user_sgpr_private_segment_size 0
		.amdhsa_uses_dynamic_stack 0
		.amdhsa_enable_private_segment 0
		.amdhsa_system_sgpr_workgroup_id_x 1
		.amdhsa_system_sgpr_workgroup_id_y 0
		.amdhsa_system_sgpr_workgroup_id_z 0
		.amdhsa_system_sgpr_workgroup_info 0
		.amdhsa_system_vgpr_workitem_id 2
		.amdhsa_next_free_vgpr 255
		.amdhsa_next_free_sgpr 100
		.amdhsa_accum_offset 256
		.amdhsa_reserve_vcc 1
		.amdhsa_float_round_mode_32 0
		.amdhsa_float_round_mode_16_64 0
		.amdhsa_float_denorm_mode_32 3
		.amdhsa_float_denorm_mode_16_64 3
		.amdhsa_dx10_clamp 1
		.amdhsa_ieee_mode 1
		.amdhsa_fp16_overflow 0
		.amdhsa_tg_split 0
		.amdhsa_exception_fp_ieee_invalid_op 0
		.amdhsa_exception_fp_denorm_src 0
		.amdhsa_exception_fp_ieee_div_zero 0
		.amdhsa_exception_fp_ieee_overflow 0
		.amdhsa_exception_fp_ieee_underflow 0
		.amdhsa_exception_fp_ieee_inexact 0
		.amdhsa_exception_int_div_zero 0
	.end_amdhsa_kernel

; __global__ void __launch_bounds__(512, 2) fwd_mega(Args a) {
;     extern __shared__ __attribute__((aligned(16))) unsigned char lds[];
;     cg::grid_group grid = cg::this_grid();
;     const int wave = __builtin_amdgcn_readfirstlane((int)threadIdx.x >> 6);
amdhsa.kernels:
  - .agpr_count:     0
    .args:
      - .offset:         0
        .size:           160
        .value_kind:     by_value
      - .offset:         160
        .size:           4
        .value_kind:     hidden_block_count_x
      - .offset:         164
        .size:           4
        .value_kind:     hidden_block_count_y
      - .offset:         168
        .size:           4
        .value_kind:     hidden_block_count_z
      - .offset:         172
        .size:           2
        .value_kind:     hidden_group_size_x
      - .offset:         174
        .size:           2
        .value_kind:     hidden_group_size_y
      - .offset:         176
        .size:           2
        .value_kind:     hidden_group_size_z
      - .offset:         178
        .size:           2
        .value_kind:     hidden_remainder_x
      - .offset:         180
        .size:           2
        .value_kind:     hidden_remainder_y
      - .offset:         182
        .size:           2
        .value_kind:     hidden_remainder_z
      - .offset:         200
        .size:           8
        .value_kind:     hidden_global_offset_x
      - .offset:         208
        .size:           8
        .value_kind:     hidden_global_offset_y
      - .offset:         216
        .size:           8
        .value_kind:     hidden_global_offset_z
      - .offset:         224
        .size:           2
        .value_kind:     hidden_grid_dims
      - .offset:         248
        .size:           8
        .value_kind:     hidden_multigrid_sync_arg
      - .offset:         280
        .size:           4
        .value_kind:     hidden_dynamic_lds_size
    .group_segment_fixed_size: 0
    .kernarg_segment_align: 8
    .kernarg_segment_size: 416
    .language:       OpenCL C
    .language_version:
      - 2
      - 0
    .max_flat_workgroup_size: 512
    .name:           _Z8fwd_mega4Args
    .private_segment_fixed_size: 0
    .sgpr_count:     106
    .sgpr_spill_count: 64
    .symbol:         _Z8fwd_mega4Args.kd
    .uniform_work_group_size: 1
    .uses_dynamic_stack: false
    .vgpr_count:     255
    .vgpr_spill_count: 0
    .wavefront_size: 64
